# RWKV prepper: wait for next-block LoRA-input loads after barrier X instead of before it (on top of CM load hoisting)
# speedup vs baseline: 1.0024x; 1.0024x over previous
.LBB0_304:
	s_or_b64 exec, exec, s[2:3]
	v_and_b32_e32 v7, 15, v7
	v_lshl_or_b32 v10, v10, 4, v7
	v_lshrrev_b32_e32 v0, 1, v6
	v_and_b32_e32 v20, 24, v0
	v_add_u32_e32 v0, v10, v8
	v_readlane_b32 s4, v254, 53
	v_ashrrev_i32_e32 v1, 31, v0
	v_readlane_b32 s5, v254, 54
	v_readlane_b32 s6, v254, 55
	v_readlane_b32 s7, v254, 56
	v_readlane_b32 s8, v254, 57
	v_readlane_b32 s9, v254, 58
	v_readlane_b32 s10, v254, 59
	v_readlane_b32 s11, v254, 60
	v_readlane_b32 s12, v254, 61
	v_readlane_b32 s13, v254, 62
	v_readlane_b32 s14, v254, 63
	v_readlane_b32 s15, v255, 0
	v_readlane_b32 s16, v255, 1
	v_readlane_b32 s17, v255, 2
	v_readlane_b32 s18, v255, 3
	v_readlane_b32 s19, v255, 4
	v_lshl_add_u64 v[0:1], v[0:1], 2, s[4:5]
	v_readlane_b32 s4, v254, 21
	v_readlane_b32 s6, v254, 23
	v_readlane_b32 s7, v254, 24
	v_add_u32_e32 v22, v10, v9
	v_lshlrev_b32_e32 v2, 1, v8
	v_mov_b64_e32 v[4:5], s[6:7]
	v_mad_i64_i32 v[4:5], s[2:3], v22, s87, v[4:5]
	v_lshl_add_u64 v[4:5], v[4:5], 0, v[2:3]
	v_mov_b32_e32 v21, v3
	v_lshl_add_u64 v[24:25], v[4:5], 0, v[20:21]
	s_movk_i32 s2, 0x1000
	v_add_co_u32_e32 v4, vcc, s2, v24
	s_waitcnt lgkmcnt(0)
	s_nop 0
	v_addc_co_u32_e32 v5, vcc, 0, v25, vcc
	s_barrier
	global_load_dword v0, v[0:1], off
	s_nop 0
	global_load_dwordx2 v[44:45], v[4:5], off offset:2592
	global_load_dwordx2 v[26:27], v[4:5], off offset:544
	global_load_dwordx2 v[178:179], v[4:5], off offset:2624
	global_load_dwordx2 v[180:181], v[4:5], off offset:576
	global_load_dwordx2 v[182:183], v[4:5], off offset:2656
	global_load_dwordx2 v[184:185], v[4:5], off offset:608
	global_load_dwordx2 v[186:187], v[4:5], off offset:2688
	global_load_dwordx2 v[188:189], v[4:5], off offset:640
	global_load_dwordx2 v[190:191], v[4:5], off offset:2720
	global_load_dwordx2 v[192:193], v[4:5], off offset:672
	global_load_dwordx2 v[194:195], v[4:5], off offset:2752
	global_load_dwordx2 v[196:197], v[4:5], off offset:704
	global_load_dwordx2 v[198:199], v[4:5], off offset:2784
	global_load_dwordx2 v[200:201], v[4:5], off offset:736
	global_load_dwordx2 v[202:203], v[4:5], off offset:2816
	global_load_dwordx2 v[204:205], v[4:5], off offset:768
	v_and_b32_e32 v1, 48, v6
	v_add_u32_e32 v8, 0, v1
	s_movk_i32 s2, 0x110
	v_mad_u32_u24 v1, v7, s2, v8
	ds_read_b128 v[4:7], v1 offset:34816
	v_mad_u64_u32 v[40:41], s[2:3], v10, s2, v[8:9]
	ds_read_b128 v[16:19], v40
	ds_read_b128 v[28:31], v1 offset:34880
	ds_read_b128 v[12:15], v40 offset:64
	ds_read_b128 v[32:35], v1 offset:34944
	s_waitcnt lgkmcnt(3)
	v_mfma_f32_16x16x32_f16 v[36:39], v[4:7], v[16:19], 0
	ds_read_b128 v[8:11], v40 offset:128
	ds_read_b128 v[4:7], v40 offset:192
	ds_read_b128 v[40:43], v1 offset:35008
	v_ashrrev_i32_e32 v23, 31, v22
	v_readlane_b32 s5, v254, 22
	s_waitcnt lgkmcnt(4)
	v_mfma_f32_16x16x32_f16 v[28:31], v[28:31], v[12:15], v[36:39]
	v_lshlrev_b64 v[22:23], 12, v[22:23]
	v_lshl_add_u64 v[22:23], s[4:5], 0, v[22:23]
	s_mov_b64 s[2:3], 0x1a20
	s_waitcnt lgkmcnt(2)
	v_mfma_f32_16x16x32_f16 v[28:31], v[32:35], v[8:11], v[28:31]
	v_lshl_add_u64 v[32:33], v[22:23], 0, v[2:3]
	v_lshl_add_u64 v[20:21], v[32:33], 0, v[20:21]
	v_lshl_add_u64 v[22:23], v[24:25], 0, s[2:3]
	s_waitcnt lgkmcnt(0)
	v_mfma_f32_16x16x32_f16 v[28:31], v[40:43], v[4:7], v[28:31]
	s_mov_b64 s[2:3], 0x1220
	v_lshl_add_u64 v[24:25], v[24:25], 0, s[2:3]
	v_readlane_b32 s8, v254, 25
	v_readlane_b32 s9, v254, 26
	v_readlane_b32 s10, v254, 27
	v_readlane_b32 s11, v254, 28
	v_readlane_b32 s12, v254, 29
	v_readlane_b32 s13, v254, 30
	v_readlane_b32 s14, v254, 31
	v_readlane_b32 s15, v254, 32
	v_readlane_b32 s16, v254, 33
	v_readlane_b32 s17, v254, 34
	v_readlane_b32 s18, v254, 35
	v_readlane_b32 s19, v254, 36
	s_waitcnt vmcnt(16)
	v_pk_add_f32 v[28:29], v[28:29], v[0:1] op_sel_hi:[1,0]
	s_waitcnt vmcnt(15)
	v_cvt_f32_f16_e32 v32, v44
	v_cvt_f32_f16_sdwa v33, v44 dst_sel:DWORD dst_unused:UNUSED_PAD src0_sel:WORD_1
	v_cvt_f32_f16_e32 v36, v45
	v_cvt_f32_f16_sdwa v37, v45 dst_sel:DWORD dst_unused:UNUSED_PAD src0_sel:WORD_1
	v_mul_f32_e32 v2, 0xbfb8aa3b, v32
	v_mul_f32_e32 v38, 0xbfb8aa3b, v33
	v_mul_f32_e32 v39, 0xbfb8aa3b, v36
	v_mul_f32_e32 v40, 0xbfb8aa3b, v37
	v_exp_f32_e32 v2, v2
	v_exp_f32_e32 v38, v38
	v_exp_f32_e32 v39, v39
	v_exp_f32_e32 v40, v40
	v_add_f32_e32 v2, 1.0, v2
	v_add_f32_e32 v41, 1.0, v38
	v_add_f32_e32 v42, 1.0, v39
	v_add_f32_e32 v43, 1.0, v40
	s_waitcnt vmcnt(14)
	v_cvt_f32_f16_e32 v34, v26
	v_cvt_f32_f16_sdwa v35, v26 dst_sel:DWORD dst_unused:UNUSED_PAD src0_sel:WORD_1
	v_cvt_f32_f16_e32 v26, v27
	v_cvt_f32_f16_sdwa v27, v27 dst_sel:DWORD dst_unused:UNUSED_PAD src0_sel:WORD_1
	v_rcp_f32_e32 v38, v2
	v_rcp_f32_e32 v39, v41
	v_rcp_f32_e32 v40, v42
	v_rcp_f32_e32 v41, v43
	v_pk_add_f32 v[30:31], v[30:31], v[0:1] op_sel_hi:[1,0]
	v_pk_mul_f32 v[28:29], v[28:29], v[34:35]
	v_pk_mul_f32 v[26:27], v[30:31], v[26:27]
	v_pk_mul_f32 v[30:31], v[38:39], v[32:33]
	v_pk_mul_f32 v[32:33], v[40:41], v[36:37]
	v_pk_mul_f32 v[28:29], v[28:29], v[30:31]
	v_pk_mul_f32 v[26:27], v[26:27], v[32:33]
	v_cvt_pk_f16_f32 v28, v28, v29
	v_cvt_pk_f16_f32 v29, v26, v27
	global_store_dwordx2 v[20:21], v[28:29], off offset:1536
	ds_read_b128 v[26:29], v1 offset:39168
	ds_read_b128 v[30:33], v1 offset:39232
	s_waitcnt lgkmcnt(1)
	v_mfma_f32_16x16x32_f16 v[26:29], v[26:29], v[16:19], 0
	s_waitcnt lgkmcnt(0)
	v_mfma_f32_16x16x32_f16 v[26:29], v[30:33], v[12:15], v[26:29]
	ds_read_b128 v[30:33], v1 offset:39296
	s_waitcnt lgkmcnt(0)
	v_mfma_f32_16x16x32_f16 v[26:29], v[30:33], v[8:11], v[26:29]
	ds_read_b128 v[30:33], v1 offset:39360
	s_waitcnt lgkmcnt(0)
	v_mfma_f32_16x16x32_f16 v[26:29], v[30:33], v[4:7], v[26:29]
	s_waitcnt vmcnt(14)
	v_cvt_f32_f16_e32 v30, v178
	v_cvt_f32_f16_sdwa v31, v178 dst_sel:DWORD dst_unused:UNUSED_PAD src0_sel:WORD_1
	v_cvt_f32_f16_e32 v34, v179
	v_cvt_f32_f16_sdwa v35, v179 dst_sel:DWORD dst_unused:UNUSED_PAD src0_sel:WORD_1
	v_mul_f32_e32 v2, 0xbfb8aa3b, v30
	v_mul_f32_e32 v38, 0xbfb8aa3b, v31
	v_mul_f32_e32 v39, 0xbfb8aa3b, v34
	v_mul_f32_e32 v40, 0xbfb8aa3b, v35
	v_exp_f32_e32 v2, v2
	v_exp_f32_e32 v38, v38
	v_exp_f32_e32 v39, v39
	v_exp_f32_e32 v40, v40
	v_add_f32_e32 v2, 1.0, v2
	v_add_f32_e32 v41, 1.0, v38
	v_add_f32_e32 v42, 1.0, v39
	v_add_f32_e32 v43, 1.0, v40
	s_waitcnt vmcnt(13)
	v_cvt_f32_f16_e32 v32, v180
	v_cvt_f32_f16_sdwa v33, v180 dst_sel:DWORD dst_unused:UNUSED_PAD src0_sel:WORD_1
	v_cvt_f32_f16_e32 v36, v181
	v_cvt_f32_f16_sdwa v37, v181 dst_sel:DWORD dst_unused:UNUSED_PAD src0_sel:WORD_1
	v_rcp_f32_e32 v38, v2
	v_rcp_f32_e32 v39, v41
	v_rcp_f32_e32 v40, v42
	v_rcp_f32_e32 v41, v43
	v_pk_add_f32 v[26:27], v[26:27], v[0:1] op_sel_hi:[1,0]
	v_pk_add_f32 v[28:29], v[28:29], v[0:1] op_sel_hi:[1,0]
	v_pk_mul_f32 v[26:27], v[26:27], v[32:33]
	v_pk_mul_f32 v[28:29], v[28:29], v[36:37]
	v_pk_mul_f32 v[30:31], v[38:39], v[30:31]
	v_pk_mul_f32 v[32:33], v[40:41], v[34:35]
	v_pk_mul_f32 v[26:27], v[26:27], v[30:31]
	v_pk_mul_f32 v[28:29], v[28:29], v[32:33]
	v_cvt_pk_f16_f32 v26, v26, v27
	v_cvt_pk_f16_f32 v27, v28, v29
	global_store_dwordx2 v[20:21], v[26:27], off offset:1568
	ds_read_b128 v[26:29], v1 offset:43520
	ds_read_b128 v[30:33], v1 offset:43584
	s_waitcnt lgkmcnt(1)
	v_mfma_f32_16x16x32_f16 v[26:29], v[26:29], v[16:19], 0
	s_waitcnt lgkmcnt(0)
	v_mfma_f32_16x16x32_f16 v[26:29], v[30:33], v[12:15], v[26:29]
	ds_read_b128 v[30:33], v1 offset:43648
	s_waitcnt lgkmcnt(0)
	v_mfma_f32_16x16x32_f16 v[26:29], v[30:33], v[8:11], v[26:29]
	ds_read_b128 v[30:33], v1 offset:43712
	s_waitcnt lgkmcnt(0)
	v_mfma_f32_16x16x32_f16 v[26:29], v[30:33], v[4:7], v[26:29]
	s_waitcnt vmcnt(13)
	v_cvt_f32_f16_e32 v30, v182
	v_cvt_f32_f16_sdwa v31, v182 dst_sel:DWORD dst_unused:UNUSED_PAD src0_sel:WORD_1
	v_cvt_f32_f16_e32 v34, v183
	v_cvt_f32_f16_sdwa v35, v183 dst_sel:DWORD dst_unused:UNUSED_PAD src0_sel:WORD_1
	v_mul_f32_e32 v2, 0xbfb8aa3b, v30
	v_mul_f32_e32 v38, 0xbfb8aa3b, v31
	v_mul_f32_e32 v39, 0xbfb8aa3b, v34
	v_mul_f32_e32 v40, 0xbfb8aa3b, v35
	v_exp_f32_e32 v2, v2
	v_exp_f32_e32 v38, v38
	v_exp_f32_e32 v39, v39
	v_exp_f32_e32 v40, v40
	v_add_f32_e32 v2, 1.0, v2
	v_add_f32_e32 v41, 1.0, v38
	v_add_f32_e32 v42, 1.0, v39
	v_add_f32_e32 v43, 1.0, v40
	s_waitcnt vmcnt(12)
	v_cvt_f32_f16_e32 v32, v184
	v_cvt_f32_f16_sdwa v33, v184 dst_sel:DWORD dst_unused:UNUSED_PAD src0_sel:WORD_1
	v_cvt_f32_f16_e32 v36, v185
	v_cvt_f32_f16_sdwa v37, v185 dst_sel:DWORD dst_unused:UNUSED_PAD src0_sel:WORD_1
	v_rcp_f32_e32 v38, v2
	v_rcp_f32_e32 v39, v41
	v_rcp_f32_e32 v40, v42
	v_rcp_f32_e32 v41, v43
	v_pk_add_f32 v[26:27], v[26:27], v[0:1] op_sel_hi:[1,0]
	v_pk_add_f32 v[28:29], v[28:29], v[0:1] op_sel_hi:[1,0]
	v_pk_mul_f32 v[26:27], v[26:27], v[32:33]
	v_pk_mul_f32 v[28:29], v[28:29], v[36:37]
	v_pk_mul_f32 v[30:31], v[38:39], v[30:31]
	v_pk_mul_f32 v[32:33], v[40:41], v[34:35]
	v_pk_mul_f32 v[26:27], v[26:27], v[30:31]
	v_pk_mul_f32 v[28:29], v[28:29], v[32:33]
	v_cvt_pk_f16_f32 v26, v26, v27
	v_cvt_pk_f16_f32 v27, v28, v29
	global_store_dwordx2 v[20:21], v[26:27], off offset:1600
	ds_read_b128 v[26:29], v1 offset:47872
	ds_read_b128 v[30:33], v1 offset:47936
	s_waitcnt lgkmcnt(1)
	v_mfma_f32_16x16x32_f16 v[26:29], v[26:29], v[16:19], 0
	s_waitcnt lgkmcnt(0)
	v_mfma_f32_16x16x32_f16 v[26:29], v[30:33], v[12:15], v[26:29]
	ds_read_b128 v[30:33], v1 offset:48000
	s_waitcnt lgkmcnt(0)
	v_mfma_f32_16x16x32_f16 v[26:29], v[30:33], v[8:11], v[26:29]
	ds_read_b128 v[30:33], v1 offset:48064
	s_waitcnt lgkmcnt(0)
	v_mfma_f32_16x16x32_f16 v[26:29], v[30:33], v[4:7], v[26:29]
	s_waitcnt vmcnt(12)
	v_cvt_f32_f16_e32 v30, v186
	v_cvt_f32_f16_sdwa v31, v186 dst_sel:DWORD dst_unused:UNUSED_PAD src0_sel:WORD_1
	v_cvt_f32_f16_e32 v34, v187
	v_cvt_f32_f16_sdwa v35, v187 dst_sel:DWORD dst_unused:UNUSED_PAD src0_sel:WORD_1
	v_mul_f32_e32 v2, 0xbfb8aa3b, v30
	v_mul_f32_e32 v38, 0xbfb8aa3b, v31
	v_mul_f32_e32 v39, 0xbfb8aa3b, v34
	v_mul_f32_e32 v40, 0xbfb8aa3b, v35
	v_exp_f32_e32 v2, v2
	v_exp_f32_e32 v38, v38
	v_exp_f32_e32 v39, v39
	v_exp_f32_e32 v40, v40
	v_add_f32_e32 v2, 1.0, v2
	v_add_f32_e32 v41, 1.0, v38
	v_add_f32_e32 v42, 1.0, v39
	v_add_f32_e32 v43, 1.0, v40
	s_waitcnt vmcnt(11)
	v_cvt_f32_f16_e32 v32, v188
	v_cvt_f32_f16_sdwa v33, v188 dst_sel:DWORD dst_unused:UNUSED_PAD src0_sel:WORD_1
	v_cvt_f32_f16_e32 v36, v189
	v_cvt_f32_f16_sdwa v37, v189 dst_sel:DWORD dst_unused:UNUSED_PAD src0_sel:WORD_1
	v_rcp_f32_e32 v38, v2
	v_rcp_f32_e32 v39, v41
	v_rcp_f32_e32 v40, v42
	v_rcp_f32_e32 v41, v43
	v_pk_add_f32 v[26:27], v[26:27], v[0:1] op_sel_hi:[1,0]
	v_pk_add_f32 v[28:29], v[28:29], v[0:1] op_sel_hi:[1,0]
	v_pk_mul_f32 v[26:27], v[26:27], v[32:33]
	v_pk_mul_f32 v[28:29], v[28:29], v[36:37]
	v_pk_mul_f32 v[30:31], v[38:39], v[30:31]
	v_pk_mul_f32 v[32:33], v[40:41], v[34:35]
	v_pk_mul_f32 v[26:27], v[26:27], v[30:31]
	v_pk_mul_f32 v[28:29], v[28:29], v[32:33]
	v_cvt_pk_f16_f32 v26, v26, v27
	v_cvt_pk_f16_f32 v27, v28, v29
	global_store_dwordx2 v[20:21], v[26:27], off offset:1632
	ds_read_b128 v[26:29], v1 offset:52224
	ds_read_b128 v[30:33], v1 offset:52288
	s_waitcnt lgkmcnt(1)
	v_mfma_f32_16x16x32_f16 v[26:29], v[26:29], v[16:19], 0
	s_waitcnt lgkmcnt(0)
	v_mfma_f32_16x16x32_f16 v[26:29], v[30:33], v[12:15], v[26:29]
	ds_read_b128 v[30:33], v1 offset:52352
	s_waitcnt lgkmcnt(0)
	v_mfma_f32_16x16x32_f16 v[26:29], v[30:33], v[8:11], v[26:29]
	ds_read_b128 v[30:33], v1 offset:52416
	s_waitcnt lgkmcnt(0)
	v_mfma_f32_16x16x32_f16 v[26:29], v[30:33], v[4:7], v[26:29]
	s_waitcnt vmcnt(11)
	v_cvt_f32_f16_e32 v30, v190
	v_cvt_f32_f16_sdwa v31, v190 dst_sel:DWORD dst_unused:UNUSED_PAD src0_sel:WORD_1
	v_cvt_f32_f16_e32 v34, v191
	v_cvt_f32_f16_sdwa v35, v191 dst_sel:DWORD dst_unused:UNUSED_PAD src0_sel:WORD_1
	v_mul_f32_e32 v2, 0xbfb8aa3b, v30
	v_mul_f32_e32 v38, 0xbfb8aa3b, v31
	v_mul_f32_e32 v39, 0xbfb8aa3b, v34
	v_mul_f32_e32 v40, 0xbfb8aa3b, v35
	v_exp_f32_e32 v2, v2
	v_exp_f32_e32 v38, v38
	v_exp_f32_e32 v39, v39
	v_exp_f32_e32 v40, v40
	v_add_f32_e32 v2, 1.0, v2
	v_add_f32_e32 v41, 1.0, v38
	v_add_f32_e32 v42, 1.0, v39
	v_add_f32_e32 v43, 1.0, v40
	s_waitcnt vmcnt(10)
	v_cvt_f32_f16_e32 v32, v192
	v_cvt_f32_f16_sdwa v33, v192 dst_sel:DWORD dst_unused:UNUSED_PAD src0_sel:WORD_1
	v_cvt_f32_f16_e32 v36, v193
	v_cvt_f32_f16_sdwa v37, v193 dst_sel:DWORD dst_unused:UNUSED_PAD src0_sel:WORD_1
	v_rcp_f32_e32 v38, v2
	v_rcp_f32_e32 v39, v41
	v_rcp_f32_e32 v40, v42
	v_rcp_f32_e32 v41, v43
	v_pk_add_f32 v[26:27], v[26:27], v[0:1] op_sel_hi:[1,0]
	v_pk_add_f32 v[28:29], v[28:29], v[0:1] op_sel_hi:[1,0]
	v_pk_mul_f32 v[26:27], v[26:27], v[32:33]
	v_pk_mul_f32 v[28:29], v[28:29], v[36:37]
	v_pk_mul_f32 v[30:31], v[38:39], v[30:31]
	v_pk_mul_f32 v[32:33], v[40:41], v[34:35]
	v_pk_mul_f32 v[26:27], v[26:27], v[30:31]
	v_pk_mul_f32 v[28:29], v[28:29], v[32:33]
	v_cvt_pk_f16_f32 v26, v26, v27
	v_cvt_pk_f16_f32 v27, v28, v29
	global_store_dwordx2 v[20:21], v[26:27], off offset:1664
	ds_read_b128 v[26:29], v1 offset:56576
	ds_read_b128 v[30:33], v1 offset:56640
	s_waitcnt lgkmcnt(1)
	v_mfma_f32_16x16x32_f16 v[26:29], v[26:29], v[16:19], 0
	s_waitcnt lgkmcnt(0)
	v_mfma_f32_16x16x32_f16 v[26:29], v[30:33], v[12:15], v[26:29]
	ds_read_b128 v[30:33], v1 offset:56704
	s_waitcnt lgkmcnt(0)
	v_mfma_f32_16x16x32_f16 v[26:29], v[30:33], v[8:11], v[26:29]
	ds_read_b128 v[30:33], v1 offset:56768
	s_waitcnt lgkmcnt(0)
	v_mfma_f32_16x16x32_f16 v[26:29], v[30:33], v[4:7], v[26:29]
	s_waitcnt vmcnt(10)
	v_cvt_f32_f16_e32 v30, v194
	v_cvt_f32_f16_sdwa v31, v194 dst_sel:DWORD dst_unused:UNUSED_PAD src0_sel:WORD_1
	v_cvt_f32_f16_e32 v34, v195
	v_cvt_f32_f16_sdwa v35, v195 dst_sel:DWORD dst_unused:UNUSED_PAD src0_sel:WORD_1
	v_mul_f32_e32 v2, 0xbfb8aa3b, v30
	v_mul_f32_e32 v38, 0xbfb8aa3b, v31
	v_mul_f32_e32 v39, 0xbfb8aa3b, v34
	v_mul_f32_e32 v40, 0xbfb8aa3b, v35
	v_exp_f32_e32 v2, v2
	v_exp_f32_e32 v38, v38
	v_exp_f32_e32 v39, v39
	v_exp_f32_e32 v40, v40
	v_add_f32_e32 v2, 1.0, v2
	v_add_f32_e32 v41, 1.0, v38
	v_add_f32_e32 v42, 1.0, v39
	v_add_f32_e32 v43, 1.0, v40
	s_waitcnt vmcnt(9)
	v_cvt_f32_f16_e32 v32, v196
	v_cvt_f32_f16_sdwa v33, v196 dst_sel:DWORD dst_unused:UNUSED_PAD src0_sel:WORD_1
	v_cvt_f32_f16_e32 v36, v197
	v_cvt_f32_f16_sdwa v37, v197 dst_sel:DWORD dst_unused:UNUSED_PAD src0_sel:WORD_1
	v_rcp_f32_e32 v38, v2
	v_rcp_f32_e32 v39, v41
	v_rcp_f32_e32 v40, v42
	v_rcp_f32_e32 v41, v43
	v_pk_add_f32 v[26:27], v[26:27], v[0:1] op_sel_hi:[1,0]
	v_pk_add_f32 v[28:29], v[28:29], v[0:1] op_sel_hi:[1,0]
	v_pk_mul_f32 v[26:27], v[26:27], v[32:33]
	v_pk_mul_f32 v[28:29], v[28:29], v[36:37]
	v_pk_mul_f32 v[30:31], v[38:39], v[30:31]
	v_pk_mul_f32 v[32:33], v[40:41], v[34:35]
	v_pk_mul_f32 v[26:27], v[26:27], v[30:31]
	v_pk_mul_f32 v[28:29], v[28:29], v[32:33]
	v_cvt_pk_f16_f32 v26, v26, v27
	v_cvt_pk_f16_f32 v27, v28, v29
	global_store_dwordx2 v[20:21], v[26:27], off offset:1696
	s_nop 0
	ds_read_b128 v[30:33], v1 offset:60928
	ds_read_b128 v[34:37], v1 offset:60992
	s_waitcnt lgkmcnt(1)
	v_mfma_f32_16x16x32_f16 v[30:33], v[30:33], v[16:19], 0
	s_waitcnt lgkmcnt(0)
	v_mfma_f32_16x16x32_f16 v[30:33], v[34:37], v[12:15], v[30:33]
	ds_read_b128 v[34:37], v1 offset:61056
	s_waitcnt lgkmcnt(0)
	v_mfma_f32_16x16x32_f16 v[30:33], v[34:37], v[8:11], v[30:33]
	ds_read_b128 v[34:37], v1 offset:61120
	s_waitcnt lgkmcnt(0)
	v_mfma_f32_16x16x32_f16 v[30:33], v[34:37], v[4:7], v[30:33]
	s_waitcnt vmcnt(9)
	v_cvt_f32_f16_e32 v34, v198
	v_cvt_f32_f16_sdwa v35, v198 dst_sel:DWORD dst_unused:UNUSED_PAD src0_sel:WORD_1
	v_cvt_f32_f16_e32 v28, v199
	v_cvt_f32_f16_sdwa v29, v199 dst_sel:DWORD dst_unused:UNUSED_PAD src0_sel:WORD_1
	v_mul_f32_e32 v2, 0xbfb8aa3b, v34
	v_mul_f32_e32 v38, 0xbfb8aa3b, v35
	v_mul_f32_e32 v39, 0xbfb8aa3b, v28
	v_mul_f32_e32 v40, 0xbfb8aa3b, v29
	v_exp_f32_e32 v2, v2
	v_exp_f32_e32 v38, v38
	v_exp_f32_e32 v39, v39
	v_exp_f32_e32 v40, v40
	v_add_f32_e32 v2, 1.0, v2
	v_add_f32_e32 v41, 1.0, v38
	v_add_f32_e32 v42, 1.0, v39
	v_add_f32_e32 v43, 1.0, v40
	s_waitcnt vmcnt(8)
	v_cvt_f32_f16_e32 v36, v200
	v_cvt_f32_f16_sdwa v37, v200 dst_sel:DWORD dst_unused:UNUSED_PAD src0_sel:WORD_1
	v_cvt_f32_f16_e32 v26, v201
	v_cvt_f32_f16_sdwa v27, v201 dst_sel:DWORD dst_unused:UNUSED_PAD src0_sel:WORD_1
	v_rcp_f32_e32 v38, v2
	v_rcp_f32_e32 v39, v41
	v_rcp_f32_e32 v40, v42
	v_rcp_f32_e32 v41, v43
	v_pk_add_f32 v[30:31], v[30:31], v[0:1] op_sel_hi:[1,0]
	v_pk_add_f32 v[32:33], v[32:33], v[0:1] op_sel_hi:[1,0]
	v_pk_mul_f32 v[30:31], v[30:31], v[36:37]
	v_pk_mul_f32 v[26:27], v[32:33], v[26:27]
	v_pk_mul_f32 v[32:33], v[38:39], v[34:35]
	v_pk_mul_f32 v[28:29], v[40:41], v[28:29]
	v_pk_mul_f32 v[30:31], v[30:31], v[32:33]
	v_pk_mul_f32 v[26:27], v[26:27], v[28:29]
	v_cvt_pk_f16_f32 v28, v30, v31
	v_cvt_pk_f16_f32 v29, v26, v27
	global_store_dwordx2 v[20:21], v[28:29], off offset:1728
	s_nop 0
	ds_read_b128 v[28:31], v1 offset:65280
	s_waitcnt lgkmcnt(0)
	v_mfma_f32_16x16x32_f16 v[16:19], v[28:31], v[16:19], 0
	ds_read_b128 v[28:31], v1 offset:65344
	s_waitcnt lgkmcnt(0)
	v_mfma_f32_16x16x32_f16 v[12:15], v[28:31], v[12:15], v[16:19]
	s_nop 4
	ds_read_b128 v[16:19], v1 offset:65408
	s_waitcnt lgkmcnt(0)
	v_mfma_f32_16x16x32_f16 v[8:11], v[16:19], v[8:11], v[12:15]
	s_nop 2
	ds_read_b128 v[12:15], v1 offset:65472
	s_waitcnt lgkmcnt(0)
	v_mfma_f32_16x16x32_f16 v[4:7], v[12:15], v[4:7], v[8:11]
	s_waitcnt vmcnt(8)
	s_nop 1
	v_cvt_f32_f16_e32 v10, v203
	s_nop 3
	v_pk_add_f32 v[4:5], v[4:5], v[0:1] op_sel_hi:[1,0]
	v_pk_add_f32 v[0:1], v[6:7], v[0:1] op_sel_hi:[1,0]
	v_cvt_f32_f16_e32 v6, v202
	v_cvt_f32_f16_sdwa v7, v202 dst_sel:DWORD dst_unused:UNUSED_PAD src0_sel:WORD_1
	v_cvt_f32_f16_sdwa v11, v203 dst_sel:DWORD dst_unused:UNUSED_PAD src0_sel:WORD_1
	v_mul_f32_e32 v15, 0xbfb8aa3b, v10
	v_mul_f32_e32 v2, 0xbfb8aa3b, v6
	v_mul_f32_e32 v14, 0xbfb8aa3b, v7
	v_mul_f32_e32 v16, 0xbfb8aa3b, v11
	v_exp_f32_e32 v2, v2
	v_exp_f32_e32 v14, v14
	v_exp_f32_e32 v15, v15
	v_exp_f32_e32 v16, v16
	v_add_f32_e32 v2, 1.0, v2
	v_add_f32_e32 v17, 1.0, v14
	v_add_f32_e32 v18, 1.0, v15
	v_add_f32_e32 v19, 1.0, v16
	s_waitcnt vmcnt(7)
	v_cvt_f32_f16_e32 v8, v204
	v_cvt_f32_f16_sdwa v9, v204 dst_sel:DWORD dst_unused:UNUSED_PAD src0_sel:WORD_1
	v_cvt_f32_f16_e32 v12, v205
	v_cvt_f32_f16_sdwa v13, v205 dst_sel:DWORD dst_unused:UNUSED_PAD src0_sel:WORD_1
	v_rcp_f32_e32 v14, v2
	v_rcp_f32_e32 v15, v17
	v_rcp_f32_e32 v16, v18
	v_rcp_f32_e32 v17, v19
	v_pk_mul_f32 v[4:5], v[4:5], v[8:9]
	v_pk_mul_f32 v[0:1], v[0:1], v[12:13]
	v_pk_mul_f32 v[6:7], v[14:15], v[6:7]
	v_pk_mul_f32 v[8:9], v[16:17], v[10:11]
	v_pk_mul_f32 v[4:5], v[4:5], v[6:7]
	v_pk_mul_f32 v[0:1], v[0:1], v[8:9]
	v_cvt_pk_f16_f32 v4, v4, v5
	v_cvt_pk_f16_f32 v5, v0, v1
	global_store_dwordx2 v[20:21], v[4:5], off offset:1760
	s_barrier

.LBB0_367:
	v_cndmask_b32_e64 v246, v240, v2, s[6:7]
	v_cndmask_b32_e64 v247, v245, v237, s[6:7]
	v_cndmask_b32_e64 v248, v2, v240, s[6:7]
	v_cndmask_b32_e64 v249, v237, v245, s[6:7]
	v_cndmask_b32_e64 v250, v243, v241, s[6:7]
	v_cndmask_b32_e64 v251, v244, v242, s[6:7]
	s_waitcnt lgkmcnt(14)
	v_mfma_f32_16x16x32_f16 v[76:79], v[76:79], v[246:249], 0
	v_cndmask_b32_e64 v252, v241, v243, s[6:7]
	v_cndmask_b32_e64 v253, v242, v244, s[6:7]
	v_add_u32_e32 v2, s77, v172
	s_waitcnt lgkmcnt(13)
	v_mfma_f32_16x16x32_f16 v[84:87], v[84:87], v[16:19], 0
	v_subrev_u32_e32 v2, 32, v2
	v_mfma_f32_16x16x32_f16 v[76:79], v[40:43], v[250:253], v[76:79]
	s_waitcnt lgkmcnt(11)
	v_mfma_f32_16x16x32_f16 v[40:43], v[48:51], v[246:249], 0
	v_mfma_f32_16x16x32_f16 v[84:87], v[44:47], v[12:15], v[84:87]
	s_waitcnt lgkmcnt(9)
	v_mfma_f32_16x16x32_f16 v[44:47], v[68:71], v[16:19], 0
	v_mfma_f32_16x16x32_f16 v[52:55], v[52:55], v[250:253], v[40:43]
	s_waitcnt lgkmcnt(7)
	v_mfma_f32_16x16x32_f16 v[40:43], v[60:63], v[246:249], 0
	v_mfma_f32_16x16x32_f16 v[56:59], v[56:59], v[12:15], v[44:47]
	s_waitcnt lgkmcnt(5)
	v_mfma_f32_16x16x32_f16 v[44:47], v[80:83], v[16:19], 0
	v_mfma_f32_16x16x32_f16 v[68:71], v[64:67], v[250:253], v[40:43]
	s_waitcnt lgkmcnt(3)
	v_mfma_f32_16x16x32_f16 v[40:43], v[88:91], v[246:249], 0
	s_waitcnt lgkmcnt(1)
	v_mfma_f32_16x16x32_f16 v[16:19], v[96:99], v[16:19], 0
	v_mfma_f32_16x16x32_f16 v[72:75], v[72:75], v[12:15], v[44:47]
	s_waitcnt lgkmcnt(0)
	v_mfma_f32_16x16x32_f16 v[64:67], v[92:95], v[12:15], v[16:19]
	s_nop 0
	v_add_u32_e32 v44, s76, v234
	v_cndmask_b32_e64 v2, v44, v2, s[2:3]
	v_mfma_f32_16x16x32_f16 v[80:83], v[36:39], v[250:253], v[40:43]
	s_branch .LBB0_378

.LBB0_378:
	s_add_i32 s26, s26, 1
	s_andn2_b64 vcc, exec, s[28:29]
	s_barrier
	s_cbranch_vccnz .LBB0_382
	s_waitcnt vmcnt(6)
	v_mov_b64_e32 v[12:13], v[100:101]
	v_mov_b64_e32 v[16:17], v[104:105]
	v_mov_b64_e32 v[18:19], v[106:107]
	v_mov_b64_e32 v[14:15], v[102:103]
	global_load_dwordx4 v[88:91], v[130:131], off
	global_load_dwordx4 v[92:95], v[132:133], off
	global_load_dwordx4 v[96:99], v[130:131], off offset:64
	global_load_dwordx4 v[100:103], v[132:133], off offset:64
	global_load_dwordx4 v[60:63], v[134:135], off
	global_load_dwordx4 v[104:107], v[134:135], off offset:64
	global_load_dwordx4 v[48:51], v[136:137], off
	global_load_dwordx4 v[40:43], v[136:137], off offset:64
	global_load_dwordx4 v[44:47], v[138:139], off
	global_load_dwordx4 v[36:39], v[138:139], off offset:64
	v_cndmask_b32_e64 v71, v71, v79, s[6:7]
	v_cndmask_b32_e64 v70, v70, v78, s[6:7]
	v_cndmask_b32_e64 v69, v69, v77, s[6:7]
	v_cndmask_b32_e64 v68, v68, v76, s[6:7]
	v_cndmask_b32_e64 v74, v74, v86, s[6:7]
	v_cndmask_b32_e64 v73, v73, v85, s[6:7]
	v_cndmask_b32_e64 v72, v72, v84, s[6:7]
	v_cndmask_b32_e64 v52, v80, v52, s[6:7]
	v_cndmask_b32_e64 v76, v83, v55, s[6:7]
	v_cndmask_b32_e64 v77, v82, v54, s[6:7]
	v_cndmask_b32_e64 v78, v81, v53, s[6:7]
	v_cndmask_b32_e64 v59, v67, v59, s[6:7]
	v_cndmask_b32_e64 v58, v66, v58, s[6:7]
	v_cndmask_b32_e64 v57, v65, v57, s[6:7]
	v_cndmask_b32_e64 v53, v64, v56, s[6:7]
	v_cndmask_b32_e64 v75, v75, v87, s[6:7]
	s_and_b32 s28, s26, 1
	s_lshl_b32 s27, s28, 13
	s_add_i32 s27, s27, 0
	v_mov_b32_e32 v84, s27
	v_cvt_f32_f16_sdwa v85, v118 dst_sel:DWORD dst_unused:UNUSED_PAD src0_sel:WORD_1
	v_cvt_f32_f16_sdwa v87, v119 dst_sel:DWORD dst_unused:UNUSED_PAD src0_sel:WORD_1
	v_cvt_f32_f16_e32 v86, v119
	v_cmp_lt_i32_e32 vcc, v157, v158
	v_cvt_f32_f16_sdwa v79, v121 dst_sel:DWORD dst_unused:UNUSED_PAD src0_sel:WORD_1
	v_cvt_f32_f16_e32 v237, v114
	v_cvt_f32_f16_sdwa v240, v114 dst_sel:DWORD dst_unused:UNUSED_PAD src0_sel:WORD_1
	v_cvt_f32_f16_e32 v241, v115
	v_cvt_f32_f16_sdwa v242, v115 dst_sel:DWORD dst_unused:UNUSED_PAD src0_sel:WORD_1
	s_waitcnt vmcnt(5)
	v_pk_mul_f32 v[62:63], v[62:63], v[86:87]
	v_add_f32_e32 v54, v68, v88
	v_add_f32_e32 v55, v72, v92
	v_add_f32_e32 v56, v69, v89
	v_add_f32_e32 v64, v73, v93
	v_add_f32_e32 v65, v70, v90
	v_add_f32_e32 v66, v74, v94
	v_add_f32_e32 v67, v71, v91
	v_add_f32_e32 v52, v52, v96
	v_add_f32_e32 v69, v53, v100
	v_mul_f32_e32 v53, 0xbfb8aa3b, v54
	v_mul_f32_e32 v54, 0xbfb8aa3b, v55
	v_mul_f32_e32 v55, 0xbfb8aa3b, v56
	v_mul_f32_e32 v56, 0xbfb8aa3b, v64
	v_mul_f32_e32 v64, 0xbfb8aa3b, v65
	v_mul_f32_e32 v65, 0xbfb8aa3b, v66
	v_mul_f32_e32 v66, 0xbfb8aa3b, v67
	v_mul_f32_e32 v52, 0xbfb8aa3b, v52
	v_exp_f32_e32 v53, v53
	v_exp_f32_e32 v54, v54
	v_exp_f32_e32 v55, v55
	v_exp_f32_e32 v56, v56
	v_exp_f32_e32 v64, v64
	v_exp_f32_e32 v66, v66
	v_exp_f32_e32 v52, v52
	v_exp_f32_e32 v65, v65
	v_add_f32_e32 v68, v75, v95
	v_mul_f32_e32 v67, 0xbfb8aa3b, v68
	v_add_f32_e32 v53, 1.0, v53
	v_add_f32_e32 v54, 1.0, v54
	v_add_f32_e32 v55, 1.0, v55
	v_add_f32_e32 v56, 1.0, v56
	v_add_f32_e32 v68, 1.0, v64
	v_add_f32_e32 v71, 1.0, v66
	v_add_f32_e32 v52, 1.0, v52
	v_add_f32_e32 v70, 1.0, v65
	v_rcp_f32_e32 v53, v53
	v_rcp_f32_e32 v64, v54
	v_rcp_f32_e32 v54, v55
	v_rcp_f32_e32 v65, v56
	v_rcp_f32_e32 v55, v68
	v_rcp_f32_e32 v56, v71
	v_rcp_f32_e32 v52, v52
	v_mul_f32_e32 v53, 0xbf1b4598, v53
	v_mul_f32_e32 v54, 0xbf1b4598, v54
	v_mul_f32_e32 v55, 0xbf1b4598, v55
	v_mul_f32_e32 v56, 0xbf1b4598, v56
	v_mul_f32_e32 v52, 0xbf1b4598, v52
	v_mul_f32_e32 v53, 0x3fb8aa3b, v53
	v_mul_f32_e32 v54, 0x3fb8aa3b, v54
	v_mul_f32_e32 v55, 0x3fb8aa3b, v55
	v_mul_f32_e32 v56, 0x3fb8aa3b, v56
	v_mul_f32_e32 v68, 0x3fb8aa3b, v52
	v_exp_f32_e32 v52, v53
	v_exp_f32_e32 v53, v54
	v_exp_f32_e32 v54, v55
	v_exp_f32_e32 v55, v56
	v_exp_f32_e32 v56, v68
	v_mul_f32_e32 v68, 0xbfb8aa3b, v69
	v_add_f32_e32 v69, v78, v97
	v_mul_f32_e32 v69, 0xbfb8aa3b, v69
	v_exp_f32_e32 v69, v69
	v_add_f32_e32 v57, v57, v101
	v_mul_f32_e32 v57, 0xbfb8aa3b, v57
	v_rcp_f32_e32 v66, v70
	v_add_f32_e32 v69, 1.0, v69
	v_rcp_f32_e32 v69, v69
	v_exp_f32_e32 v70, v57
	v_add_f32_e32 v58, v58, v102
	v_mul_f32_e32 v58, 0xbfb8aa3b, v58
	v_mul_f32_e32 v57, 0xbf1b4598, v69
	v_add_f32_e32 v69, 1.0, v70
	v_add_f32_e32 v70, v77, v98
	v_mul_f32_e32 v70, 0xbfb8aa3b, v70
	v_exp_f32_e32 v72, v70
	v_exp_f32_e32 v78, v58
	v_add_f32_e32 v58, v76, v99
	v_mul_f32_e32 v58, 0xbfb8aa3b, v58
	v_add_f32_e32 v72, 1.0, v72
	v_rcp_f32_e32 v77, v72
	v_exp_f32_e32 v76, v58
	v_mad_u32_u24 v96, s28, v167, v84
	v_cvt_f32_f16_e32 v84, v118
	v_mul_f32_e32 v77, 0xbf1b4598, v77
	v_add_f32_e32 v76, 1.0, v76
	v_mul_f32_e32 v58, 0x3fb8aa3b, v77
	v_add_f32_e32 v77, 1.0, v78
	v_rcp_f32_e32 v78, v76
	v_cvt_f32_f16_sdwa v71, v120 dst_sel:DWORD dst_unused:UNUSED_PAD src0_sel:WORD_1
	v_cvt_f32_f16_e32 v70, v120
	v_add_f32_e32 v59, v59, v103
	v_mul_f32_e32 v59, 0xbfb8aa3b, v59
	v_cndmask_b32_e32 v88, v156, v157, vcc
	v_pk_mul_f32 v[60:61], v[60:61], v[84:85]
	v_rcp_f32_e32 v76, v77
	v_mul_f32_e32 v77, 0xbf1b4598, v78
	v_exp_f32_e32 v80, v59
	v_cvt_f32_f16_e32 v78, v121
	v_lshlrev_b32_e32 v97, 2, v88
	v_pk_mul_f32 v[88:89], v[60:61], v[60:61]
	v_pk_mul_f32 v[90:91], v[62:63], v[62:63]
	v_add_f32_e32 v88, v88, v89
	s_waitcnt vmcnt(4)
	v_pk_mul_f32 v[72:73], v[104:105], v[70:71]
	v_add_f32_e32 v88, v90, v88
	v_pk_mul_f32 v[74:75], v[72:73], v[72:73]
	v_mul_f32_e32 v77, 0x3fb8aa3b, v77
	v_add_f32_e32 v88, v91, v88
	v_exp_f32_e32 v59, v77
	v_add_f32_e32 v77, 1.0, v80
	v_pk_mul_f32 v[80:81], v[106:107], v[78:79]
	v_add_f32_e32 v74, v88, v74
	v_pk_mul_f32 v[82:83], v[80:81], v[80:81]
	v_add_f32_e32 v74, v75, v74
	v_add_f32_e32 v74, v82, v74
	v_add_f32_e32 v74, v83, v74
	v_cmp_lt_i32_e32 vcc, v159, v158
	v_exp_f32_e32 v67, v67
	v_add_f32_dpp v82, v74, v74 row_ror:8 row_mask:0xf bank_mask:0xf bound_ctrl:1
	ds_bpermute_b32 v83, v97, v82
	v_cndmask_b32_e32 v74, v156, v159, vcc
	v_lshlrev_b32_e32 v88, 2, v74
	v_pk_add_f32 v[74:75], v[64:65], -1.0 op_sel_hi:[1,0]
	v_add_f32_e32 v67, 1.0, v67
	s_waitcnt lgkmcnt(0)
	v_add_f32_e32 v82, v82, v83
	ds_bpermute_b32 v83, v88, v82
	s_waitcnt vmcnt(3)
	v_pk_fma_f32 v[48:49], v[48:49], v[74:75], 1.0 op_sel_hi:[1,1,0]
	v_rcp_f32_e32 v67, v67
	v_pk_mul_f32 v[48:49], v[48:49], v[84:85]
	v_exp_f32_e32 v68, v68
	v_mul_f32_e32 v74, v48, v237
	s_waitcnt vmcnt(1)
	v_fma_f32 v84, v44, v74, 0
	s_waitcnt lgkmcnt(0)
	v_add_f32_e32 v44, v82, v83
	v_max_f32_e32 v44, 0x179abe15, v44
	v_rsq_f32_e32 v44, v44
	v_mul_f32_e32 v74, v49, v240
	v_add_f32_e32 v68, 1.0, v68
	v_fmac_f32_e32 v84, v45, v74
	v_pk_mul_f32 v[62:63], v[62:63], v[44:45] op_sel_hi:[1,0]
	v_rcp_f32_e32 v68, v68
	v_pk_mul_f32 v[74:75], v[66:67], v[62:63]
	v_pk_add_f32 v[66:67], v[66:67], -1.0 op_sel_hi:[1,0]
	v_rcp_f32_e32 v69, v69
	v_pk_fma_f32 v[50:51], v[50:51], v[66:67], 1.0 op_sel_hi:[1,1,0]
	v_pk_mul_f32 v[60:61], v[60:61], v[44:45] op_sel_hi:[1,0]
	v_pk_mul_f32 v[50:51], v[50:51], v[86:87]
	v_cvt_f32_f16_e32 v92, v110
	v_mul_f32_e32 v45, v50, v241
	v_cvt_pk_f16_f32 v48, v48, v49
	v_mul_f32_e32 v49, v51, v242
	v_fmac_f32_e32 v84, v46, v45
	v_cvt_f32_f16_sdwa v93, v110 dst_sel:DWORD dst_unused:UNUSED_PAD src0_sel:WORD_1
	v_fmac_f32_e32 v84, v47, v49
	v_cvt_pk_f16_f32 v49, v50, v51
	v_lshl_add_u32 v45, v174, 2, s27
	v_pk_add_f32 v[50:51], v[68:69], -1.0 op_sel_hi:[1,0]
	v_rcp_f32_e32 v77, v77
	v_pk_mul_f32 v[64:65], v[64:65], v[60:61]
	v_cvt_pk_f16_f32 v47, -v62, -v63
	v_cvt_pk_f16_f32 v46, -v60, -v61
	ds_write_b128 v45, v[52:55]
	v_lshl_add_u32 v45, v174, 1, v96
	v_pk_fma_f32 v[40:41], v[40:41], v[50:51], 1.0 op_sel_hi:[1,1,0]
	v_cvt_pk_f16_f32 v64, v64, v65
	v_cvt_pk_f16_f32 v65, v74, v75
	ds_write2st64_b64 v45, v[48:49], v[46:47] offset0:32 offset1:40
	ds_write2st64_b64 v45, v[64:65], v[114:115] offset0:48 offset1:56
	ds_write_b64 v45, v[116:117] offset:32768
	v_pk_mul_f32 v[46:47], v[72:73], v[44:45] op_sel_hi:[1,0]
	v_pk_mul_f32 v[40:41], v[40:41], v[70:71]
	v_pk_mul_f32 v[48:49], v[68:69], v[46:47]
	v_mul_f32_e32 v45, v40, v92
	v_cvt_f32_f16_e32 v94, v111
	v_cvt_pk_f16_f32 v48, v48, v49
	v_mul_f32_e32 v49, v41, v93
	s_waitcnt vmcnt(0)
	v_fmac_f32_e32 v84, v36, v45
	v_cvt_f32_f16_sdwa v95, v111 dst_sel:DWORD dst_unused:UNUSED_PAD src0_sel:WORD_1
	v_fmac_f32_e32 v84, v37, v49
	v_pk_add_f32 v[36:37], v[76:77], -1.0 op_sel_hi:[1,0]
	v_mul_f32_e32 v57, 0x3fb8aa3b, v57
	v_pk_fma_f32 v[36:37], v[42:43], v[36:37], 1.0 op_sel_hi:[1,1,0]
	v_exp_f32_e32 v57, v57
	v_pk_mul_f32 v[42:43], v[36:37], v[78:79]
	v_exp_f32_e32 v58, v58
	v_mul_f32_e32 v36, v42, v94
	v_mul_f32_e32 v37, v43, v95
	v_fmac_f32_e32 v84, v38, v36
	v_fmac_f32_e32 v84, v39, v37
	v_cvt_pk_f16_f32 v38, v40, v41
	s_nop 0
	v_add_f32_dpp v39, v84, v84 row_ror:8 row_mask:0xf bank_mask:0xf bound_ctrl:1
	ds_bpermute_b32 v45, v97, v39
	s_waitcnt lgkmcnt(0)
	v_pk_mul_f32 v[40:41], v[80:81], v[44:45] op_sel_hi:[1,0]
	s_nop 0
	v_pk_mul_f32 v[36:37], v[76:77], v[40:41]
	v_cvt_pk_f16_f32 v41, -v40, -v41
	v_cvt_pk_f16_f32 v49, v36, v37
	v_add_f32_e32 v36, v39, v45
	ds_bpermute_b32 v37, v88, v36
	v_cvt_pk_f16_f32 v39, v42, v43
	v_lshl_add_u32 v42, v175, 2, s27
	v_cvt_pk_f16_f32 v40, -v46, -v47
	ds_write_b128 v42, v[56:59]
	v_lshl_add_u32 v42, v175, 1, v96
	ds_write2st64_b64 v42, v[38:39], v[40:41] offset0:32 offset1:40
	ds_write2st64_b64 v42, v[48:49], v[110:111] offset0:48 offset1:56
	ds_write_b64 v42, v[112:113] offset:32768
	s_and_saveexec_b64 s[28:29], s[8:9]
	s_cbranch_execz .LBB0_381
	v_add_u32_e32 v2, v2, v173
	s_waitcnt lgkmcnt(4)
	v_add_f32_e32 v38, v36, v37
	v_mad_i64_i32 v[36:37], s[30:31], v2, 48, v[128:129]
	global_store_dword v[36:37], v38, off

.LBB0_467:
	v_cndmask_b32_e64 v242, v233, v2, s[6:7]
	v_cndmask_b32_e64 v243, v240, v232, s[6:7]
	v_cndmask_b32_e64 v244, v2, v233, s[6:7]
	v_cndmask_b32_e64 v245, v232, v240, s[6:7]
	v_cndmask_b32_e64 v232, v236, v234, s[6:7]
	v_cndmask_b32_e64 v233, v237, v235, s[6:7]
	s_waitcnt lgkmcnt(14)
	v_mfma_f32_16x16x32_f16 v[76:79], v[76:79], v[242:245], 0
	v_cndmask_b32_e64 v234, v234, v236, s[6:7]
	v_cndmask_b32_e64 v235, v235, v237, s[6:7]
	v_add_u32_e32 v2, s71, v150
	s_waitcnt lgkmcnt(13)
	v_mfma_f32_16x16x32_f16 v[84:87], v[84:87], v[32:35], 0
	v_subrev_u32_e32 v2, 32, v2
	v_mfma_f32_16x16x32_f16 v[76:79], v[40:43], v[232:235], v[76:79]
	s_waitcnt lgkmcnt(11)
	v_mfma_f32_16x16x32_f16 v[40:43], v[48:51], v[242:245], 0
	v_mfma_f32_16x16x32_f16 v[84:87], v[44:47], v[28:31], v[84:87]
	s_waitcnt lgkmcnt(9)
	v_mfma_f32_16x16x32_f16 v[44:47], v[68:71], v[32:35], 0
	v_mfma_f32_16x16x32_f16 v[52:55], v[52:55], v[232:235], v[40:43]
	s_waitcnt lgkmcnt(7)
	v_mfma_f32_16x16x32_f16 v[40:43], v[60:63], v[242:245], 0
	v_mfma_f32_16x16x32_f16 v[56:59], v[56:59], v[28:31], v[44:47]
	s_waitcnt lgkmcnt(5)
	v_mfma_f32_16x16x32_f16 v[44:47], v[80:83], v[32:35], 0
	v_mfma_f32_16x16x32_f16 v[68:71], v[64:67], v[232:235], v[40:43]
	s_waitcnt lgkmcnt(3)
	v_mfma_f32_16x16x32_f16 v[40:43], v[88:91], v[242:245], 0
	s_waitcnt lgkmcnt(1)
	v_mfma_f32_16x16x32_f16 v[32:35], v[96:99], v[32:35], 0
	v_mfma_f32_16x16x32_f16 v[72:75], v[72:75], v[28:31], v[44:47]
	s_waitcnt lgkmcnt(0)
	v_mfma_f32_16x16x32_f16 v[64:67], v[92:95], v[28:31], v[32:35]
	s_nop 0
	v_add_u32_e32 v44, s70, v229
	v_cndmask_b32_e64 v2, v44, v2, s[2:3]
	v_mfma_f32_16x16x32_f16 v[80:83], v[36:39], v[232:235], v[40:43]
	s_branch .LBB0_477

.LBB0_477:
	s_add_i32 s76, s76, 1
	s_andn2_b64 vcc, exec, s[26:27]
	s_barrier
	s_cbranch_vccnz .LBB0_454
	s_waitcnt vmcnt(6)
	v_mov_b64_e32 v[28:29], v[100:101]
	v_mov_b64_e32 v[32:33], v[104:105]
	v_mov_b64_e32 v[34:35], v[106:107]
	v_mov_b64_e32 v[30:31], v[102:103]
	global_load_dwordx4 v[88:91], v[126:127], off
	global_load_dwordx4 v[92:95], v[128:129], off
	global_load_dwordx4 v[96:99], v[126:127], off offset:64
	global_load_dwordx4 v[100:103], v[128:129], off offset:64
	global_load_dwordx4 v[60:63], v[130:131], off
	global_load_dwordx4 v[104:107], v[130:131], off offset:64
	global_load_dwordx4 v[48:51], v[132:133], off
	global_load_dwordx4 v[40:43], v[132:133], off offset:64
	global_load_dwordx4 v[44:47], v[134:135], off
	global_load_dwordx4 v[36:39], v[134:135], off offset:64
	v_cndmask_b32_e64 v71, v71, v79, s[6:7]
	v_cndmask_b32_e64 v70, v70, v78, s[6:7]
	v_cndmask_b32_e64 v69, v69, v77, s[6:7]
	v_cndmask_b32_e64 v68, v68, v76, s[6:7]
	v_cndmask_b32_e64 v74, v74, v86, s[6:7]
	v_cndmask_b32_e64 v73, v73, v85, s[6:7]
	v_cndmask_b32_e64 v72, v72, v84, s[6:7]
	v_cndmask_b32_e64 v52, v80, v52, s[6:7]
	v_cndmask_b32_e64 v76, v83, v55, s[6:7]
	v_cndmask_b32_e64 v77, v82, v54, s[6:7]
	v_cndmask_b32_e64 v78, v81, v53, s[6:7]
	v_cndmask_b32_e64 v59, v67, v59, s[6:7]
	v_cndmask_b32_e64 v58, v66, v58, s[6:7]
	v_cndmask_b32_e64 v57, v65, v57, s[6:7]
	v_cndmask_b32_e64 v53, v64, v56, s[6:7]
	v_cndmask_b32_e64 v75, v75, v87, s[6:7]
	s_and_b32 s27, s76, 1
	s_lshl_b32 s26, s27, 13
	s_add_i32 s26, s26, 0
	v_mov_b32_e32 v84, s26
	v_cvt_f32_f16_sdwa v85, v116 dst_sel:DWORD dst_unused:UNUSED_PAD src0_sel:WORD_1
	v_cvt_f32_f16_sdwa v87, v117 dst_sel:DWORD dst_unused:UNUSED_PAD src0_sel:WORD_1
	v_cvt_f32_f16_e32 v86, v117
	v_cmp_lt_i32_e32 vcc, v157, v158
	v_cvt_f32_f16_sdwa v79, v119 dst_sel:DWORD dst_unused:UNUSED_PAD src0_sel:WORD_1
	v_cvt_f32_f16_e32 v232, v112
	v_cvt_f32_f16_sdwa v233, v112 dst_sel:DWORD dst_unused:UNUSED_PAD src0_sel:WORD_1
	v_cvt_f32_f16_e32 v234, v113
	v_cvt_f32_f16_sdwa v235, v113 dst_sel:DWORD dst_unused:UNUSED_PAD src0_sel:WORD_1
	s_waitcnt vmcnt(5)
	v_pk_mul_f32 v[62:63], v[62:63], v[86:87]
	v_add_f32_e32 v54, v68, v88
	v_add_f32_e32 v55, v72, v92
	v_add_f32_e32 v56, v69, v89
	v_add_f32_e32 v64, v73, v93
	v_add_f32_e32 v65, v70, v90
	v_add_f32_e32 v66, v74, v94
	v_add_f32_e32 v67, v71, v91
	v_add_f32_e32 v52, v52, v96
	v_add_f32_e32 v69, v53, v100
	v_mul_f32_e32 v53, 0xbfb8aa3b, v54
	v_mul_f32_e32 v54, 0xbfb8aa3b, v55
	v_mul_f32_e32 v55, 0xbfb8aa3b, v56
	v_mul_f32_e32 v56, 0xbfb8aa3b, v64
	v_mul_f32_e32 v64, 0xbfb8aa3b, v65
	v_mul_f32_e32 v65, 0xbfb8aa3b, v66
	v_mul_f32_e32 v66, 0xbfb8aa3b, v67
	v_mul_f32_e32 v52, 0xbfb8aa3b, v52
	v_exp_f32_e32 v53, v53
	v_exp_f32_e32 v54, v54
	v_exp_f32_e32 v55, v55
	v_exp_f32_e32 v56, v56
	v_exp_f32_e32 v64, v64
	v_exp_f32_e32 v66, v66
	v_exp_f32_e32 v52, v52
	v_exp_f32_e32 v65, v65
	v_add_f32_e32 v68, v75, v95
	v_mul_f32_e32 v67, 0xbfb8aa3b, v68
	v_add_f32_e32 v53, 1.0, v53
	v_add_f32_e32 v54, 1.0, v54
	v_add_f32_e32 v55, 1.0, v55
	v_add_f32_e32 v56, 1.0, v56
	v_add_f32_e32 v68, 1.0, v64
	v_add_f32_e32 v71, 1.0, v66
	v_add_f32_e32 v52, 1.0, v52
	v_add_f32_e32 v70, 1.0, v65
	v_rcp_f32_e32 v53, v53
	v_rcp_f32_e32 v64, v54
	v_rcp_f32_e32 v54, v55
	v_rcp_f32_e32 v65, v56
	v_rcp_f32_e32 v55, v68
	v_rcp_f32_e32 v56, v71
	v_rcp_f32_e32 v52, v52
	v_mul_f32_e32 v53, 0xbf1b4598, v53
	v_mul_f32_e32 v54, 0xbf1b4598, v54
	v_mul_f32_e32 v55, 0xbf1b4598, v55
	v_mul_f32_e32 v56, 0xbf1b4598, v56
	v_mul_f32_e32 v52, 0xbf1b4598, v52
	v_mul_f32_e32 v53, 0x3fb8aa3b, v53
	v_mul_f32_e32 v54, 0x3fb8aa3b, v54
	v_mul_f32_e32 v55, 0x3fb8aa3b, v55
	v_mul_f32_e32 v56, 0x3fb8aa3b, v56
	v_mul_f32_e32 v68, 0x3fb8aa3b, v52
	v_exp_f32_e32 v52, v53
	v_exp_f32_e32 v53, v54
	v_exp_f32_e32 v54, v55
	v_exp_f32_e32 v55, v56
	v_exp_f32_e32 v56, v68
	v_mul_f32_e32 v68, 0xbfb8aa3b, v69
	v_add_f32_e32 v69, v78, v97
	v_mul_f32_e32 v69, 0xbfb8aa3b, v69
	v_exp_f32_e32 v69, v69
	v_add_f32_e32 v57, v57, v101
	v_mul_f32_e32 v57, 0xbfb8aa3b, v57
	v_rcp_f32_e32 v66, v70
	v_add_f32_e32 v69, 1.0, v69
	v_rcp_f32_e32 v69, v69
	v_exp_f32_e32 v70, v57
	v_add_f32_e32 v58, v58, v102
	v_mul_f32_e32 v58, 0xbfb8aa3b, v58
	v_mul_f32_e32 v57, 0xbf1b4598, v69
	v_add_f32_e32 v69, 1.0, v70
	v_add_f32_e32 v70, v77, v98
	v_mul_f32_e32 v70, 0xbfb8aa3b, v70
	v_exp_f32_e32 v72, v70
	v_exp_f32_e32 v78, v58
	v_add_f32_e32 v58, v76, v99
	v_mul_f32_e32 v58, 0xbfb8aa3b, v58
	v_add_f32_e32 v72, 1.0, v72
	v_rcp_f32_e32 v77, v72
	v_exp_f32_e32 v76, v58
	v_mad_u32_u24 v96, s27, v167, v84
	v_cvt_f32_f16_e32 v84, v116
	v_mul_f32_e32 v77, 0xbf1b4598, v77
	v_add_f32_e32 v76, 1.0, v76
	v_mul_f32_e32 v58, 0x3fb8aa3b, v77
	v_add_f32_e32 v77, 1.0, v78
	v_rcp_f32_e32 v78, v76
	v_cvt_f32_f16_sdwa v71, v118 dst_sel:DWORD dst_unused:UNUSED_PAD src0_sel:WORD_1
	v_cvt_f32_f16_e32 v70, v118
	v_add_f32_e32 v59, v59, v103
	v_mul_f32_e32 v59, 0xbfb8aa3b, v59
	v_cndmask_b32_e32 v88, v156, v157, vcc
	v_pk_mul_f32 v[60:61], v[60:61], v[84:85]
	v_rcp_f32_e32 v76, v77
	v_mul_f32_e32 v77, 0xbf1b4598, v78
	v_exp_f32_e32 v80, v59
	v_cvt_f32_f16_e32 v78, v119
	v_lshlrev_b32_e32 v97, 2, v88
	v_pk_mul_f32 v[88:89], v[60:61], v[60:61]
	v_pk_mul_f32 v[90:91], v[62:63], v[62:63]
	v_add_f32_e32 v88, v88, v89
	s_waitcnt vmcnt(4)
	v_pk_mul_f32 v[72:73], v[104:105], v[70:71]
	v_add_f32_e32 v88, v90, v88
	v_pk_mul_f32 v[74:75], v[72:73], v[72:73]
	v_mul_f32_e32 v77, 0x3fb8aa3b, v77
	v_add_f32_e32 v88, v91, v88
	v_exp_f32_e32 v59, v77
	v_add_f32_e32 v77, 1.0, v80
	v_pk_mul_f32 v[80:81], v[106:107], v[78:79]
	v_add_f32_e32 v74, v88, v74
	v_pk_mul_f32 v[82:83], v[80:81], v[80:81]
	v_add_f32_e32 v74, v75, v74
	v_add_f32_e32 v74, v82, v74
	v_add_f32_e32 v74, v83, v74
	v_cmp_lt_i32_e32 vcc, v159, v158
	v_exp_f32_e32 v67, v67
	v_add_f32_dpp v82, v74, v74 row_ror:8 row_mask:0xf bank_mask:0xf bound_ctrl:1
	ds_bpermute_b32 v83, v97, v82
	v_cndmask_b32_e32 v74, v156, v159, vcc
	v_lshlrev_b32_e32 v88, 2, v74
	v_pk_add_f32 v[74:75], v[64:65], -1.0 op_sel_hi:[1,0]
	v_add_f32_e32 v67, 1.0, v67
	s_waitcnt lgkmcnt(0)
	v_add_f32_e32 v82, v82, v83
	ds_bpermute_b32 v83, v88, v82
	s_waitcnt vmcnt(3)
	v_pk_fma_f32 v[48:49], v[48:49], v[74:75], 1.0 op_sel_hi:[1,1,0]
	v_rcp_f32_e32 v67, v67
	v_pk_mul_f32 v[48:49], v[48:49], v[84:85]
	v_exp_f32_e32 v68, v68
	v_mul_f32_e32 v74, v48, v232
	s_waitcnt vmcnt(1)
	v_fma_f32 v84, v44, v74, 0
	s_waitcnt lgkmcnt(0)
	v_add_f32_e32 v44, v82, v83
	v_max_f32_e32 v44, 0x179abe15, v44
	v_rsq_f32_e32 v44, v44
	v_mul_f32_e32 v74, v49, v233
	v_add_f32_e32 v68, 1.0, v68
	v_fmac_f32_e32 v84, v45, v74
	v_pk_mul_f32 v[62:63], v[62:63], v[44:45] op_sel_hi:[1,0]
	v_rcp_f32_e32 v68, v68
	v_pk_mul_f32 v[74:75], v[66:67], v[62:63]
	v_pk_add_f32 v[66:67], v[66:67], -1.0 op_sel_hi:[1,0]
	v_rcp_f32_e32 v69, v69
	v_pk_fma_f32 v[50:51], v[50:51], v[66:67], 1.0 op_sel_hi:[1,1,0]
	v_pk_mul_f32 v[60:61], v[60:61], v[44:45] op_sel_hi:[1,0]
	v_pk_mul_f32 v[50:51], v[50:51], v[86:87]
	v_cvt_f32_f16_e32 v92, v108
	v_mul_f32_e32 v45, v50, v234
	v_cvt_pk_f16_f32 v48, v48, v49
	v_mul_f32_e32 v49, v51, v235
	v_fmac_f32_e32 v84, v46, v45
	v_cvt_f32_f16_sdwa v93, v108 dst_sel:DWORD dst_unused:UNUSED_PAD src0_sel:WORD_1
	v_fmac_f32_e32 v84, v47, v49
	v_cvt_pk_f16_f32 v49, v50, v51
	v_lshl_add_u32 v45, v152, 2, s26
	v_pk_add_f32 v[50:51], v[68:69], -1.0 op_sel_hi:[1,0]
	v_rcp_f32_e32 v77, v77
	v_pk_mul_f32 v[64:65], v[64:65], v[60:61]
	v_cvt_pk_f16_f32 v47, -v62, -v63
	v_cvt_pk_f16_f32 v46, -v60, -v61
	ds_write_b128 v45, v[52:55]
	v_lshl_add_u32 v45, v152, 1, v96
	v_pk_fma_f32 v[40:41], v[40:41], v[50:51], 1.0 op_sel_hi:[1,1,0]
	v_cvt_pk_f16_f32 v64, v64, v65
	v_cvt_pk_f16_f32 v65, v74, v75
	ds_write2st64_b64 v45, v[48:49], v[46:47] offset0:32 offset1:40
	ds_write2st64_b64 v45, v[64:65], v[112:113] offset0:48 offset1:56
	ds_write_b64 v45, v[114:115] offset:32768
	v_pk_mul_f32 v[46:47], v[72:73], v[44:45] op_sel_hi:[1,0]
	v_pk_mul_f32 v[40:41], v[40:41], v[70:71]
	v_pk_mul_f32 v[48:49], v[68:69], v[46:47]
	v_mul_f32_e32 v45, v40, v92
	v_cvt_f32_f16_e32 v94, v109
	v_cvt_pk_f16_f32 v48, v48, v49
	v_mul_f32_e32 v49, v41, v93
	s_waitcnt vmcnt(0)
	v_fmac_f32_e32 v84, v36, v45
	v_cvt_f32_f16_sdwa v95, v109 dst_sel:DWORD dst_unused:UNUSED_PAD src0_sel:WORD_1
	v_fmac_f32_e32 v84, v37, v49
	v_pk_add_f32 v[36:37], v[76:77], -1.0 op_sel_hi:[1,0]
	v_mul_f32_e32 v57, 0x3fb8aa3b, v57
	v_pk_fma_f32 v[36:37], v[42:43], v[36:37], 1.0 op_sel_hi:[1,1,0]
	v_exp_f32_e32 v57, v57
	v_pk_mul_f32 v[42:43], v[36:37], v[78:79]
	v_exp_f32_e32 v58, v58
	v_mul_f32_e32 v36, v42, v94
	v_mul_f32_e32 v37, v43, v95
	v_fmac_f32_e32 v84, v38, v36
	v_fmac_f32_e32 v84, v39, v37
	v_cvt_pk_f16_f32 v38, v40, v41
	s_nop 0
	v_add_f32_dpp v39, v84, v84 row_ror:8 row_mask:0xf bank_mask:0xf bound_ctrl:1
	ds_bpermute_b32 v45, v97, v39
	s_waitcnt lgkmcnt(0)
	v_pk_mul_f32 v[40:41], v[80:81], v[44:45] op_sel_hi:[1,0]
	s_nop 0
	v_pk_mul_f32 v[36:37], v[76:77], v[40:41]
	v_cvt_pk_f16_f32 v41, -v40, -v41
	v_cvt_pk_f16_f32 v49, v36, v37
	v_add_f32_e32 v36, v39, v45
	ds_bpermute_b32 v37, v88, v36
	v_cvt_pk_f16_f32 v39, v42, v43
	v_lshl_add_u32 v42, v171, 2, s26
	v_cvt_pk_f16_f32 v40, -v46, -v47
	ds_write_b128 v42, v[56:59]
	v_lshl_add_u32 v42, v171, 1, v96
	ds_write2st64_b64 v42, v[38:39], v[40:41] offset0:32 offset1:40
	ds_write2st64_b64 v42, v[48:49], v[108:109] offset0:48 offset1:56
	ds_write_b64 v42, v[110:111] offset:32768
	s_and_saveexec_b64 s[26:27], s[8:9]
	s_cbranch_execz .LBB0_480
	v_add_u32_e32 v2, v2, v151
	s_waitcnt lgkmcnt(4)
	v_add_f32_e32 v38, v36, v37
	v_mad_i64_i32 v[36:37], s[28:29], v2, 48, v[124:125]
	global_store_dword v[36:37], v38, off

.LBB0_877:
	s_or_b64 exec, exec, s[2:3]
	v_and_b32_e32 v12, 15, v8
	v_lshl_or_b32 v11, v11, 4, v12
	v_lshrrev_b32_e32 v0, 1, v6
	v_and_b32_e32 v20, 24, v0
	v_lshl_add_u32 v0, v7, 7, v11
	v_readlane_b32 s4, v254, 53
	v_ashrrev_i32_e32 v1, 31, v0
	v_readlane_b32 s5, v254, 54
	v_readlane_b32 s6, v254, 55
	v_readlane_b32 s7, v254, 56
	v_readlane_b32 s8, v254, 57
	v_readlane_b32 s9, v254, 58
	v_readlane_b32 s10, v254, 59
	v_readlane_b32 s11, v254, 60
	v_readlane_b32 s12, v254, 61
	v_readlane_b32 s13, v254, 62
	v_readlane_b32 s14, v254, 63
	v_readlane_b32 s15, v255, 0
	v_readlane_b32 s16, v255, 1
	v_readlane_b32 s17, v255, 2
	v_readlane_b32 s18, v255, 3
	v_readlane_b32 s19, v255, 4
	v_lshl_add_u64 v[0:1], v[0:1], 2, s[4:5]
	v_readlane_b32 s4, v254, 21
	v_readlane_b32 s6, v254, 23
	v_readlane_b32 s7, v254, 24
	v_add_u32_e32 v22, v11, v10
	v_lshlrev_b32_e32 v2, 1, v9
	v_mov_b64_e32 v[4:5], s[6:7]
	v_mad_i64_i32 v[4:5], s[2:3], v22, s71, v[4:5]
	v_lshl_add_u64 v[4:5], v[4:5], 0, v[2:3]
	v_mov_b32_e32 v21, v3
	v_lshl_add_u64 v[24:25], v[4:5], 0, v[20:21]
	s_movk_i32 s2, 0x1000
	v_add_co_u32_e32 v4, vcc, s2, v24
	s_waitcnt lgkmcnt(0)
	s_nop 0
	v_addc_co_u32_e32 v5, vcc, 0, v25, vcc
	s_barrier
	global_load_dword v0, v[0:1], off
	s_nop 0
	global_load_dwordx2 v[42:43], v[4:5], off offset:2592
	global_load_dwordx2 v[44:45], v[4:5], off offset:544
	global_load_dwordx2 v[178:179], v[4:5], off offset:2624
	global_load_dwordx2 v[180:181], v[4:5], off offset:576
	global_load_dwordx2 v[182:183], v[4:5], off offset:2656
	global_load_dwordx2 v[184:185], v[4:5], off offset:608
	global_load_dwordx2 v[186:187], v[4:5], off offset:2688
	global_load_dwordx2 v[188:189], v[4:5], off offset:640
	global_load_dwordx2 v[190:191], v[4:5], off offset:2720
	global_load_dwordx2 v[192:193], v[4:5], off offset:672
	global_load_dwordx2 v[194:195], v[4:5], off offset:2752
	global_load_dwordx2 v[196:197], v[4:5], off offset:704
	global_load_dwordx2 v[198:199], v[4:5], off offset:2784
	global_load_dwordx2 v[200:201], v[4:5], off offset:736
	global_load_dwordx2 v[202:203], v[4:5], off offset:2816
	global_load_dwordx2 v[204:205], v[4:5], off offset:768
	v_and_b32_e32 v1, 48, v6
	v_add_u32_e32 v8, 0, v1
	v_mad_u32_u24 v1, v12, s48, v8
	ds_read_b128 v[4:7], v1 offset:34816
	v_mad_u64_u32 v[38:39], s[2:3], v11, s48, v[8:9]
	ds_read_b128 v[16:19], v38
	ds_read_b128 v[26:29], v1 offset:34880
	ds_read_b128 v[12:15], v38 offset:64
	ds_read_b128 v[30:33], v1 offset:34944
	s_waitcnt lgkmcnt(3)
	v_mfma_f32_16x16x32_f16 v[34:37], v[4:7], v[16:19], 0
	ds_read_b128 v[8:11], v38 offset:128
	ds_read_b128 v[4:7], v38 offset:192
	ds_read_b128 v[38:41], v1 offset:35008
	v_ashrrev_i32_e32 v23, 31, v22
	v_readlane_b32 s5, v254, 22
	s_waitcnt lgkmcnt(4)
	v_mfma_f32_16x16x32_f16 v[26:29], v[26:29], v[12:15], v[34:37]
	v_lshlrev_b64 v[22:23], 12, v[22:23]
	v_lshl_add_u64 v[22:23], s[4:5], 0, v[22:23]
	s_mov_b64 s[2:3], 0x1a20
	s_waitcnt lgkmcnt(2)
	v_mfma_f32_16x16x32_f16 v[26:29], v[30:33], v[8:11], v[26:29]
	v_lshl_add_u64 v[30:31], v[22:23], 0, v[2:3]
	v_lshl_add_u64 v[20:21], v[30:31], 0, v[20:21]
	v_lshl_add_u64 v[22:23], v[24:25], 0, s[2:3]
	s_waitcnt lgkmcnt(0)
	v_mfma_f32_16x16x32_f16 v[26:29], v[38:41], v[4:7], v[26:29]
	s_mov_b64 s[2:3], 0x1220
	v_lshl_add_u64 v[24:25], v[24:25], 0, s[2:3]
	v_readlane_b32 s8, v254, 25
	v_readlane_b32 s9, v254, 26
	v_readlane_b32 s10, v254, 27
	v_readlane_b32 s11, v254, 28
	v_readlane_b32 s12, v254, 29
	v_readlane_b32 s13, v254, 30
	v_readlane_b32 s14, v254, 31
	v_readlane_b32 s15, v254, 32
	v_readlane_b32 s16, v254, 33
	v_readlane_b32 s17, v254, 34
	v_readlane_b32 s18, v254, 35
	v_readlane_b32 s19, v254, 36
	s_waitcnt vmcnt(16)
	v_pk_add_f32 v[26:27], v[26:27], v[0:1] op_sel_hi:[1,0]
	s_waitcnt vmcnt(15)
	v_cvt_f32_f16_e32 v30, v42
	v_cvt_f32_f16_sdwa v31, v42 dst_sel:DWORD dst_unused:UNUSED_PAD src0_sel:WORD_1
	v_cvt_f32_f16_e32 v34, v43
	v_cvt_f32_f16_sdwa v35, v43 dst_sel:DWORD dst_unused:UNUSED_PAD src0_sel:WORD_1
	v_mul_f32_e32 v2, 0xbfb8aa3b, v30
	v_mul_f32_e32 v38, 0xbfb8aa3b, v31
	v_mul_f32_e32 v39, 0xbfb8aa3b, v34
	v_mul_f32_e32 v40, 0xbfb8aa3b, v35
	v_exp_f32_e32 v2, v2
	v_exp_f32_e32 v38, v38
	v_exp_f32_e32 v39, v39
	v_exp_f32_e32 v40, v40
	v_add_f32_e32 v2, 1.0, v2
	v_add_f32_e32 v41, 1.0, v38
	v_add_f32_e32 v42, 1.0, v39
	v_add_f32_e32 v43, 1.0, v40
	s_waitcnt vmcnt(14)
	v_cvt_f32_f16_e32 v32, v44
	v_cvt_f32_f16_sdwa v33, v44 dst_sel:DWORD dst_unused:UNUSED_PAD src0_sel:WORD_1
	v_cvt_f32_f16_e32 v36, v45
	v_cvt_f32_f16_sdwa v37, v45 dst_sel:DWORD dst_unused:UNUSED_PAD src0_sel:WORD_1
	v_rcp_f32_e32 v38, v2
	v_rcp_f32_e32 v39, v41
	v_rcp_f32_e32 v40, v42
	v_rcp_f32_e32 v41, v43
	v_pk_add_f32 v[28:29], v[28:29], v[0:1] op_sel_hi:[1,0]
	v_pk_mul_f32 v[26:27], v[26:27], v[32:33]
	v_pk_mul_f32 v[28:29], v[28:29], v[36:37]
	v_pk_mul_f32 v[30:31], v[38:39], v[30:31]
	v_pk_mul_f32 v[32:33], v[40:41], v[34:35]
	v_pk_mul_f32 v[26:27], v[26:27], v[30:31]
	v_pk_mul_f32 v[28:29], v[28:29], v[32:33]
	v_cvt_pk_f16_f32 v26, v26, v27
	v_cvt_pk_f16_f32 v27, v28, v29
	global_store_dwordx2 v[20:21], v[26:27], off offset:1536
	ds_read_b128 v[26:29], v1 offset:39168
	ds_read_b128 v[30:33], v1 offset:39232
	s_waitcnt lgkmcnt(1)
	v_mfma_f32_16x16x32_f16 v[26:29], v[26:29], v[16:19], 0
	s_waitcnt lgkmcnt(0)
	v_mfma_f32_16x16x32_f16 v[26:29], v[30:33], v[12:15], v[26:29]
	ds_read_b128 v[30:33], v1 offset:39296
	s_waitcnt lgkmcnt(0)
	v_mfma_f32_16x16x32_f16 v[26:29], v[30:33], v[8:11], v[26:29]
	ds_read_b128 v[30:33], v1 offset:39360
	s_waitcnt lgkmcnt(0)
	v_mfma_f32_16x16x32_f16 v[26:29], v[30:33], v[4:7], v[26:29]
	s_waitcnt vmcnt(14)
	v_cvt_f32_f16_e32 v30, v178
	v_cvt_f32_f16_sdwa v31, v178 dst_sel:DWORD dst_unused:UNUSED_PAD src0_sel:WORD_1
	v_cvt_f32_f16_e32 v34, v179
	v_cvt_f32_f16_sdwa v35, v179 dst_sel:DWORD dst_unused:UNUSED_PAD src0_sel:WORD_1
	v_mul_f32_e32 v2, 0xbfb8aa3b, v30
	v_mul_f32_e32 v38, 0xbfb8aa3b, v31
	v_mul_f32_e32 v39, 0xbfb8aa3b, v34
	v_mul_f32_e32 v40, 0xbfb8aa3b, v35
	v_exp_f32_e32 v2, v2
	v_exp_f32_e32 v38, v38
	v_exp_f32_e32 v39, v39
	v_exp_f32_e32 v40, v40
	v_add_f32_e32 v2, 1.0, v2
	v_add_f32_e32 v41, 1.0, v38
	v_add_f32_e32 v42, 1.0, v39
	v_add_f32_e32 v43, 1.0, v40
	s_waitcnt vmcnt(13)
	v_cvt_f32_f16_e32 v32, v180
	v_cvt_f32_f16_sdwa v33, v180 dst_sel:DWORD dst_unused:UNUSED_PAD src0_sel:WORD_1
	v_cvt_f32_f16_e32 v36, v181
	v_cvt_f32_f16_sdwa v37, v181 dst_sel:DWORD dst_unused:UNUSED_PAD src0_sel:WORD_1
	v_rcp_f32_e32 v38, v2
	v_rcp_f32_e32 v39, v41
	v_rcp_f32_e32 v40, v42
	v_rcp_f32_e32 v41, v43
	v_pk_add_f32 v[26:27], v[26:27], v[0:1] op_sel_hi:[1,0]
	v_pk_add_f32 v[28:29], v[28:29], v[0:1] op_sel_hi:[1,0]
	v_pk_mul_f32 v[26:27], v[26:27], v[32:33]
	v_pk_mul_f32 v[28:29], v[28:29], v[36:37]
	v_pk_mul_f32 v[30:31], v[38:39], v[30:31]
	v_pk_mul_f32 v[32:33], v[40:41], v[34:35]
	v_pk_mul_f32 v[26:27], v[26:27], v[30:31]
	v_pk_mul_f32 v[28:29], v[28:29], v[32:33]
	v_cvt_pk_f16_f32 v26, v26, v27
	v_cvt_pk_f16_f32 v27, v28, v29
	global_store_dwordx2 v[20:21], v[26:27], off offset:1568
	ds_read_b128 v[26:29], v1 offset:43520
	ds_read_b128 v[30:33], v1 offset:43584
	s_waitcnt lgkmcnt(1)
	v_mfma_f32_16x16x32_f16 v[26:29], v[26:29], v[16:19], 0
	s_waitcnt lgkmcnt(0)
	v_mfma_f32_16x16x32_f16 v[26:29], v[30:33], v[12:15], v[26:29]
	ds_read_b128 v[30:33], v1 offset:43648
	s_waitcnt lgkmcnt(0)
	v_mfma_f32_16x16x32_f16 v[26:29], v[30:33], v[8:11], v[26:29]
	ds_read_b128 v[30:33], v1 offset:43712
	s_waitcnt lgkmcnt(0)
	v_mfma_f32_16x16x32_f16 v[26:29], v[30:33], v[4:7], v[26:29]
	s_waitcnt vmcnt(13)
	v_cvt_f32_f16_e32 v30, v182
	v_cvt_f32_f16_sdwa v31, v182 dst_sel:DWORD dst_unused:UNUSED_PAD src0_sel:WORD_1
	v_cvt_f32_f16_e32 v34, v183
	v_cvt_f32_f16_sdwa v35, v183 dst_sel:DWORD dst_unused:UNUSED_PAD src0_sel:WORD_1
	v_mul_f32_e32 v2, 0xbfb8aa3b, v30
	v_mul_f32_e32 v38, 0xbfb8aa3b, v31
	v_mul_f32_e32 v39, 0xbfb8aa3b, v34
	v_mul_f32_e32 v40, 0xbfb8aa3b, v35
	v_exp_f32_e32 v2, v2
	v_exp_f32_e32 v38, v38
	v_exp_f32_e32 v39, v39
	v_exp_f32_e32 v40, v40
	v_add_f32_e32 v2, 1.0, v2
	v_add_f32_e32 v41, 1.0, v38
	v_add_f32_e32 v42, 1.0, v39
	v_add_f32_e32 v43, 1.0, v40
	s_waitcnt vmcnt(12)
	v_cvt_f32_f16_e32 v32, v184
	v_cvt_f32_f16_sdwa v33, v184 dst_sel:DWORD dst_unused:UNUSED_PAD src0_sel:WORD_1
	v_cvt_f32_f16_e32 v36, v185
	v_cvt_f32_f16_sdwa v37, v185 dst_sel:DWORD dst_unused:UNUSED_PAD src0_sel:WORD_1
	v_rcp_f32_e32 v38, v2
	v_rcp_f32_e32 v39, v41
	v_rcp_f32_e32 v40, v42
	v_rcp_f32_e32 v41, v43
	v_pk_add_f32 v[26:27], v[26:27], v[0:1] op_sel_hi:[1,0]
	v_pk_add_f32 v[28:29], v[28:29], v[0:1] op_sel_hi:[1,0]
	v_pk_mul_f32 v[26:27], v[26:27], v[32:33]
	v_pk_mul_f32 v[28:29], v[28:29], v[36:37]
	v_pk_mul_f32 v[30:31], v[38:39], v[30:31]
	v_pk_mul_f32 v[32:33], v[40:41], v[34:35]
	v_pk_mul_f32 v[26:27], v[26:27], v[30:31]
	v_pk_mul_f32 v[28:29], v[28:29], v[32:33]
	v_cvt_pk_f16_f32 v26, v26, v27
	v_cvt_pk_f16_f32 v27, v28, v29
	global_store_dwordx2 v[20:21], v[26:27], off offset:1600
	ds_read_b128 v[26:29], v1 offset:47872
	ds_read_b128 v[30:33], v1 offset:47936
	s_waitcnt lgkmcnt(1)
	v_mfma_f32_16x16x32_f16 v[26:29], v[26:29], v[16:19], 0
	s_waitcnt lgkmcnt(0)
	v_mfma_f32_16x16x32_f16 v[26:29], v[30:33], v[12:15], v[26:29]
	ds_read_b128 v[30:33], v1 offset:48000
	s_waitcnt lgkmcnt(0)
	v_mfma_f32_16x16x32_f16 v[26:29], v[30:33], v[8:11], v[26:29]
	ds_read_b128 v[30:33], v1 offset:48064
	s_waitcnt lgkmcnt(0)
	v_mfma_f32_16x16x32_f16 v[26:29], v[30:33], v[4:7], v[26:29]
	s_waitcnt vmcnt(12)
	v_cvt_f32_f16_e32 v30, v186
	v_cvt_f32_f16_sdwa v31, v186 dst_sel:DWORD dst_unused:UNUSED_PAD src0_sel:WORD_1
	v_cvt_f32_f16_e32 v34, v187
	v_cvt_f32_f16_sdwa v35, v187 dst_sel:DWORD dst_unused:UNUSED_PAD src0_sel:WORD_1
	v_mul_f32_e32 v2, 0xbfb8aa3b, v30
	v_mul_f32_e32 v38, 0xbfb8aa3b, v31
	v_mul_f32_e32 v39, 0xbfb8aa3b, v34
	v_mul_f32_e32 v40, 0xbfb8aa3b, v35
	v_exp_f32_e32 v2, v2
	v_exp_f32_e32 v38, v38
	v_exp_f32_e32 v39, v39
	v_exp_f32_e32 v40, v40
	v_add_f32_e32 v2, 1.0, v2
	v_add_f32_e32 v41, 1.0, v38
	v_add_f32_e32 v42, 1.0, v39
	v_add_f32_e32 v43, 1.0, v40
	s_waitcnt vmcnt(11)
	v_cvt_f32_f16_e32 v32, v188
	v_cvt_f32_f16_sdwa v33, v188 dst_sel:DWORD dst_unused:UNUSED_PAD src0_sel:WORD_1
	v_cvt_f32_f16_e32 v36, v189
	v_cvt_f32_f16_sdwa v37, v189 dst_sel:DWORD dst_unused:UNUSED_PAD src0_sel:WORD_1
	v_rcp_f32_e32 v38, v2
	v_rcp_f32_e32 v39, v41
	v_rcp_f32_e32 v40, v42
	v_rcp_f32_e32 v41, v43
	v_pk_add_f32 v[26:27], v[26:27], v[0:1] op_sel_hi:[1,0]
	v_pk_add_f32 v[28:29], v[28:29], v[0:1] op_sel_hi:[1,0]
	v_pk_mul_f32 v[26:27], v[26:27], v[32:33]
	v_pk_mul_f32 v[28:29], v[28:29], v[36:37]
	v_pk_mul_f32 v[30:31], v[38:39], v[30:31]
	v_pk_mul_f32 v[32:33], v[40:41], v[34:35]
	v_pk_mul_f32 v[26:27], v[26:27], v[30:31]
	v_pk_mul_f32 v[28:29], v[28:29], v[32:33]
	v_cvt_pk_f16_f32 v26, v26, v27
	v_cvt_pk_f16_f32 v27, v28, v29
	global_store_dwordx2 v[20:21], v[26:27], off offset:1632
	ds_read_b128 v[26:29], v1 offset:52224
	ds_read_b128 v[30:33], v1 offset:52288
	s_waitcnt lgkmcnt(1)
	v_mfma_f32_16x16x32_f16 v[26:29], v[26:29], v[16:19], 0
	s_waitcnt lgkmcnt(0)
	v_mfma_f32_16x16x32_f16 v[26:29], v[30:33], v[12:15], v[26:29]
	ds_read_b128 v[30:33], v1 offset:52352
	s_waitcnt lgkmcnt(0)
	v_mfma_f32_16x16x32_f16 v[26:29], v[30:33], v[8:11], v[26:29]
	ds_read_b128 v[30:33], v1 offset:52416
	s_waitcnt lgkmcnt(0)
	v_mfma_f32_16x16x32_f16 v[26:29], v[30:33], v[4:7], v[26:29]
	s_waitcnt vmcnt(11)
	v_cvt_f32_f16_e32 v30, v190
	v_cvt_f32_f16_sdwa v31, v190 dst_sel:DWORD dst_unused:UNUSED_PAD src0_sel:WORD_1
	v_cvt_f32_f16_e32 v34, v191
	v_cvt_f32_f16_sdwa v35, v191 dst_sel:DWORD dst_unused:UNUSED_PAD src0_sel:WORD_1
	v_mul_f32_e32 v2, 0xbfb8aa3b, v30
	v_mul_f32_e32 v38, 0xbfb8aa3b, v31
	v_mul_f32_e32 v39, 0xbfb8aa3b, v34
	v_mul_f32_e32 v40, 0xbfb8aa3b, v35
	v_exp_f32_e32 v2, v2
	v_exp_f32_e32 v38, v38
	v_exp_f32_e32 v39, v39
	v_exp_f32_e32 v40, v40
	v_add_f32_e32 v2, 1.0, v2
	v_add_f32_e32 v41, 1.0, v38
	v_add_f32_e32 v42, 1.0, v39
	v_add_f32_e32 v43, 1.0, v40
	s_waitcnt vmcnt(10)
	v_cvt_f32_f16_e32 v32, v192
	v_cvt_f32_f16_sdwa v33, v192 dst_sel:DWORD dst_unused:UNUSED_PAD src0_sel:WORD_1
	v_cvt_f32_f16_e32 v36, v193
	v_cvt_f32_f16_sdwa v37, v193 dst_sel:DWORD dst_unused:UNUSED_PAD src0_sel:WORD_1
	v_rcp_f32_e32 v38, v2
	v_rcp_f32_e32 v39, v41
	v_rcp_f32_e32 v40, v42
	v_rcp_f32_e32 v41, v43
	v_pk_add_f32 v[26:27], v[26:27], v[0:1] op_sel_hi:[1,0]
	v_pk_add_f32 v[28:29], v[28:29], v[0:1] op_sel_hi:[1,0]
	v_pk_mul_f32 v[26:27], v[26:27], v[32:33]
	v_pk_mul_f32 v[28:29], v[28:29], v[36:37]
	v_pk_mul_f32 v[30:31], v[38:39], v[30:31]
	v_pk_mul_f32 v[32:33], v[40:41], v[34:35]
	v_pk_mul_f32 v[26:27], v[26:27], v[30:31]
	v_pk_mul_f32 v[28:29], v[28:29], v[32:33]
	v_cvt_pk_f16_f32 v26, v26, v27
	v_cvt_pk_f16_f32 v27, v28, v29
	global_store_dwordx2 v[20:21], v[26:27], off offset:1664
	ds_read_b128 v[26:29], v1 offset:56576
	ds_read_b128 v[30:33], v1 offset:56640
	s_waitcnt lgkmcnt(1)
	v_mfma_f32_16x16x32_f16 v[26:29], v[26:29], v[16:19], 0
	s_waitcnt lgkmcnt(0)
	v_mfma_f32_16x16x32_f16 v[26:29], v[30:33], v[12:15], v[26:29]
	ds_read_b128 v[30:33], v1 offset:56704
	s_waitcnt lgkmcnt(0)
	v_mfma_f32_16x16x32_f16 v[26:29], v[30:33], v[8:11], v[26:29]
	ds_read_b128 v[30:33], v1 offset:56768
	s_waitcnt lgkmcnt(0)
	v_mfma_f32_16x16x32_f16 v[26:29], v[30:33], v[4:7], v[26:29]
	s_waitcnt vmcnt(10)
	v_cvt_f32_f16_e32 v30, v194
	v_cvt_f32_f16_sdwa v31, v194 dst_sel:DWORD dst_unused:UNUSED_PAD src0_sel:WORD_1
	v_cvt_f32_f16_e32 v34, v195
	v_cvt_f32_f16_sdwa v35, v195 dst_sel:DWORD dst_unused:UNUSED_PAD src0_sel:WORD_1
	v_mul_f32_e32 v2, 0xbfb8aa3b, v30
	v_mul_f32_e32 v38, 0xbfb8aa3b, v31
	v_mul_f32_e32 v39, 0xbfb8aa3b, v34
	v_mul_f32_e32 v40, 0xbfb8aa3b, v35
	v_exp_f32_e32 v2, v2
	v_exp_f32_e32 v38, v38
	v_exp_f32_e32 v39, v39
	v_exp_f32_e32 v40, v40
	v_add_f32_e32 v2, 1.0, v2
	v_add_f32_e32 v41, 1.0, v38
	v_add_f32_e32 v42, 1.0, v39
	v_add_f32_e32 v43, 1.0, v40
	s_waitcnt vmcnt(9)
	v_cvt_f32_f16_e32 v32, v196
	v_cvt_f32_f16_sdwa v33, v196 dst_sel:DWORD dst_unused:UNUSED_PAD src0_sel:WORD_1
	v_cvt_f32_f16_e32 v36, v197
	v_cvt_f32_f16_sdwa v37, v197 dst_sel:DWORD dst_unused:UNUSED_PAD src0_sel:WORD_1
	v_rcp_f32_e32 v38, v2
	v_rcp_f32_e32 v39, v41
	v_rcp_f32_e32 v40, v42
	v_rcp_f32_e32 v41, v43
	v_pk_add_f32 v[26:27], v[26:27], v[0:1] op_sel_hi:[1,0]
	v_pk_add_f32 v[28:29], v[28:29], v[0:1] op_sel_hi:[1,0]
	v_pk_mul_f32 v[26:27], v[26:27], v[32:33]
	v_pk_mul_f32 v[28:29], v[28:29], v[36:37]
	v_pk_mul_f32 v[30:31], v[38:39], v[30:31]
	v_pk_mul_f32 v[32:33], v[40:41], v[34:35]
	v_pk_mul_f32 v[26:27], v[26:27], v[30:31]
	v_pk_mul_f32 v[28:29], v[28:29], v[32:33]
	v_cvt_pk_f16_f32 v26, v26, v27
	v_cvt_pk_f16_f32 v27, v28, v29
	global_store_dwordx2 v[20:21], v[26:27], off offset:1696
	s_nop 0
	ds_read_b128 v[30:33], v1 offset:60928
	ds_read_b128 v[34:37], v1 offset:60992
	s_waitcnt lgkmcnt(1)
	v_mfma_f32_16x16x32_f16 v[30:33], v[30:33], v[16:19], 0
	s_waitcnt lgkmcnt(0)
	v_mfma_f32_16x16x32_f16 v[30:33], v[34:37], v[12:15], v[30:33]
	ds_read_b128 v[34:37], v1 offset:61056
	s_waitcnt lgkmcnt(0)
	v_mfma_f32_16x16x32_f16 v[30:33], v[34:37], v[8:11], v[30:33]
	ds_read_b128 v[34:37], v1 offset:61120
	s_waitcnt lgkmcnt(0)
	v_mfma_f32_16x16x32_f16 v[30:33], v[34:37], v[4:7], v[30:33]
	s_waitcnt vmcnt(9)
	v_cvt_f32_f16_e32 v34, v198
	v_cvt_f32_f16_sdwa v35, v198 dst_sel:DWORD dst_unused:UNUSED_PAD src0_sel:WORD_1
	v_cvt_f32_f16_e32 v28, v199
	v_cvt_f32_f16_sdwa v29, v199 dst_sel:DWORD dst_unused:UNUSED_PAD src0_sel:WORD_1
	v_mul_f32_e32 v2, 0xbfb8aa3b, v34
	v_mul_f32_e32 v38, 0xbfb8aa3b, v35
	v_mul_f32_e32 v39, 0xbfb8aa3b, v28
	v_mul_f32_e32 v40, 0xbfb8aa3b, v29
	v_exp_f32_e32 v2, v2
	v_exp_f32_e32 v38, v38
	v_exp_f32_e32 v39, v39
	v_exp_f32_e32 v40, v40
	v_add_f32_e32 v2, 1.0, v2
	v_add_f32_e32 v41, 1.0, v38
	v_add_f32_e32 v42, 1.0, v39
	v_add_f32_e32 v43, 1.0, v40
	s_waitcnt vmcnt(8)
	v_cvt_f32_f16_e32 v36, v200
	v_cvt_f32_f16_sdwa v37, v200 dst_sel:DWORD dst_unused:UNUSED_PAD src0_sel:WORD_1
	v_cvt_f32_f16_e32 v26, v201
	v_cvt_f32_f16_sdwa v27, v201 dst_sel:DWORD dst_unused:UNUSED_PAD src0_sel:WORD_1
	v_rcp_f32_e32 v38, v2
	v_rcp_f32_e32 v39, v41
	v_rcp_f32_e32 v40, v42
	v_rcp_f32_e32 v41, v43
	v_pk_add_f32 v[30:31], v[30:31], v[0:1] op_sel_hi:[1,0]
	v_pk_add_f32 v[32:33], v[32:33], v[0:1] op_sel_hi:[1,0]
	v_pk_mul_f32 v[30:31], v[30:31], v[36:37]
	v_pk_mul_f32 v[26:27], v[32:33], v[26:27]
	v_pk_mul_f32 v[32:33], v[38:39], v[34:35]
	v_pk_mul_f32 v[28:29], v[40:41], v[28:29]
	v_pk_mul_f32 v[30:31], v[30:31], v[32:33]
	v_pk_mul_f32 v[26:27], v[26:27], v[28:29]
	v_cvt_pk_f16_f32 v28, v30, v31
	v_cvt_pk_f16_f32 v29, v26, v27
	global_store_dwordx2 v[20:21], v[28:29], off offset:1728
	s_nop 0
	ds_read_b128 v[28:31], v1 offset:65280
	s_waitcnt lgkmcnt(0)
	v_mfma_f32_16x16x32_f16 v[16:19], v[28:31], v[16:19], 0
	ds_read_b128 v[28:31], v1 offset:65344
	s_waitcnt lgkmcnt(0)
	v_mfma_f32_16x16x32_f16 v[12:15], v[28:31], v[12:15], v[16:19]
	s_nop 4
	ds_read_b128 v[16:19], v1 offset:65408
	s_waitcnt lgkmcnt(0)
	v_mfma_f32_16x16x32_f16 v[8:11], v[16:19], v[8:11], v[12:15]
	s_nop 2
	ds_read_b128 v[12:15], v1 offset:65472
	s_waitcnt lgkmcnt(0)
	v_mfma_f32_16x16x32_f16 v[4:7], v[12:15], v[4:7], v[8:11]
	s_waitcnt vmcnt(8)
	s_nop 1
	v_cvt_f32_f16_e32 v10, v203
	s_nop 3
	v_pk_add_f32 v[4:5], v[4:5], v[0:1] op_sel_hi:[1,0]
	v_pk_add_f32 v[0:1], v[6:7], v[0:1] op_sel_hi:[1,0]
	v_cvt_f32_f16_e32 v6, v202
	v_cvt_f32_f16_sdwa v7, v202 dst_sel:DWORD dst_unused:UNUSED_PAD src0_sel:WORD_1
	v_cvt_f32_f16_sdwa v11, v203 dst_sel:DWORD dst_unused:UNUSED_PAD src0_sel:WORD_1
	v_mul_f32_e32 v15, 0xbfb8aa3b, v10
	v_mul_f32_e32 v2, 0xbfb8aa3b, v6
	v_mul_f32_e32 v14, 0xbfb8aa3b, v7
	v_mul_f32_e32 v16, 0xbfb8aa3b, v11
	v_exp_f32_e32 v2, v2
	v_exp_f32_e32 v14, v14
	v_exp_f32_e32 v15, v15
	v_exp_f32_e32 v16, v16
	v_add_f32_e32 v2, 1.0, v2
	v_add_f32_e32 v17, 1.0, v14
	v_add_f32_e32 v18, 1.0, v15
	v_add_f32_e32 v19, 1.0, v16
	s_waitcnt vmcnt(7)
	v_cvt_f32_f16_e32 v8, v204
	v_cvt_f32_f16_sdwa v9, v204 dst_sel:DWORD dst_unused:UNUSED_PAD src0_sel:WORD_1
	v_cvt_f32_f16_e32 v12, v205
	v_cvt_f32_f16_sdwa v13, v205 dst_sel:DWORD dst_unused:UNUSED_PAD src0_sel:WORD_1
	v_rcp_f32_e32 v14, v2
	v_rcp_f32_e32 v15, v17
	v_rcp_f32_e32 v16, v18
	v_rcp_f32_e32 v17, v19
	v_pk_mul_f32 v[4:5], v[4:5], v[8:9]
	v_pk_mul_f32 v[0:1], v[0:1], v[12:13]
	v_pk_mul_f32 v[6:7], v[14:15], v[6:7]
	v_pk_mul_f32 v[8:9], v[16:17], v[10:11]
	v_pk_mul_f32 v[4:5], v[4:5], v[6:7]
	v_pk_mul_f32 v[0:1], v[0:1], v[8:9]
	v_cvt_pk_f16_f32 v4, v4, v5
	v_cvt_pk_f16_f32 v5, v0, v1
	global_store_dwordx2 v[20:21], v[4:5], off offset:1760
	s_barrier

.LBB0_940:
	v_cndmask_b32_e64 v248, v242, v2, s[6:7]
	v_cndmask_b32_e64 v249, v247, v241, s[6:7]
	v_cndmask_b32_e64 v250, v2, v242, s[6:7]
	v_cndmask_b32_e64 v251, v241, v247, s[6:7]
	v_cndmask_b32_e64 v162, v245, v243, s[6:7]
	v_cndmask_b32_e64 v163, v246, v244, s[6:7]
	s_waitcnt lgkmcnt(14)
	v_mfma_f32_16x16x32_f16 v[76:79], v[76:79], v[248:251], 0
	v_cndmask_b32_e64 v164, v243, v245, s[6:7]
	v_cndmask_b32_e64 v165, v244, v246, s[6:7]
	v_add_u32_e32 v2, s77, v174
	s_waitcnt lgkmcnt(13)
	v_mfma_f32_16x16x32_f16 v[84:87], v[84:87], v[16:19], 0
	v_subrev_u32_e32 v2, 32, v2
	v_mfma_f32_16x16x32_f16 v[76:79], v[40:43], v[162:165], v[76:79]
	s_waitcnt lgkmcnt(11)
	v_mfma_f32_16x16x32_f16 v[40:43], v[48:51], v[248:251], 0
	v_mfma_f32_16x16x32_f16 v[84:87], v[44:47], v[12:15], v[84:87]
	s_waitcnt lgkmcnt(9)
	v_mfma_f32_16x16x32_f16 v[44:47], v[68:71], v[16:19], 0
	v_mfma_f32_16x16x32_f16 v[52:55], v[52:55], v[162:165], v[40:43]
	s_waitcnt lgkmcnt(7)
	v_mfma_f32_16x16x32_f16 v[40:43], v[60:63], v[248:251], 0
	v_mfma_f32_16x16x32_f16 v[56:59], v[56:59], v[12:15], v[44:47]
	s_waitcnt lgkmcnt(5)
	v_mfma_f32_16x16x32_f16 v[44:47], v[80:83], v[16:19], 0
	v_mfma_f32_16x16x32_f16 v[68:71], v[64:67], v[162:165], v[40:43]
	s_waitcnt lgkmcnt(3)
	v_mfma_f32_16x16x32_f16 v[40:43], v[88:91], v[248:251], 0
	s_waitcnt lgkmcnt(1)
	v_mfma_f32_16x16x32_f16 v[16:19], v[96:99], v[16:19], 0
	v_mfma_f32_16x16x32_f16 v[72:75], v[72:75], v[12:15], v[44:47]
	s_waitcnt lgkmcnt(0)
	v_mfma_f32_16x16x32_f16 v[64:67], v[92:95], v[12:15], v[16:19]
	s_nop 0
	v_add_u32_e32 v44, s76, v236
	v_cndmask_b32_e64 v2, v44, v2, s[2:3]
	v_mfma_f32_16x16x32_f16 v[80:83], v[36:39], v[162:165], v[40:43]
	s_branch .LBB0_951

.LBB0_951:
	s_add_i32 s26, s26, 1
	s_andn2_b64 vcc, exec, s[28:29]
	s_barrier
	s_cbranch_vccnz .LBB0_955
	s_waitcnt vmcnt(6)
	v_mov_b64_e32 v[12:13], v[100:101]
	v_mov_b64_e32 v[16:17], v[104:105]
	v_mov_b64_e32 v[18:19], v[106:107]
	v_mov_b64_e32 v[14:15], v[102:103]
	global_load_dwordx4 v[88:91], v[130:131], off
	global_load_dwordx4 v[92:95], v[132:133], off
	global_load_dwordx4 v[96:99], v[130:131], off offset:64
	global_load_dwordx4 v[100:103], v[132:133], off offset:64
	global_load_dwordx4 v[60:63], v[134:135], off offset:3072
	global_load_dwordx4 v[104:107], v[134:135], off offset:3136
	global_load_dwordx4 v[48:51], v[136:137], off offset:3072
	global_load_dwordx4 v[40:43], v[136:137], off offset:3136
	global_load_dwordx4 v[44:47], v[138:139], off offset:3072
	global_load_dwordx4 v[36:39], v[138:139], off offset:3136
	v_cndmask_b32_e64 v71, v71, v79, s[6:7]
	v_cndmask_b32_e64 v70, v70, v78, s[6:7]
	v_cndmask_b32_e64 v69, v69, v77, s[6:7]
	v_cndmask_b32_e64 v68, v68, v76, s[6:7]
	v_cndmask_b32_e64 v74, v74, v86, s[6:7]
	v_cndmask_b32_e64 v73, v73, v85, s[6:7]
	v_cndmask_b32_e64 v72, v72, v84, s[6:7]
	v_cndmask_b32_e64 v52, v80, v52, s[6:7]
	v_cndmask_b32_e64 v76, v83, v55, s[6:7]
	v_cndmask_b32_e64 v77, v82, v54, s[6:7]
	v_cndmask_b32_e64 v78, v81, v53, s[6:7]
	v_cndmask_b32_e64 v59, v67, v59, s[6:7]
	v_cndmask_b32_e64 v58, v66, v58, s[6:7]
	v_cndmask_b32_e64 v57, v65, v57, s[6:7]
	v_cndmask_b32_e64 v53, v64, v56, s[6:7]
	v_cndmask_b32_e64 v75, v75, v87, s[6:7]
	s_and_b32 s28, s26, 1
	s_lshl_b32 s27, s28, 13
	s_add_i32 s27, s27, 0
	v_mov_b32_e32 v84, s27
	v_cvt_f32_f16_sdwa v85, v118 dst_sel:DWORD dst_unused:UNUSED_PAD src0_sel:WORD_1
	v_cvt_f32_f16_sdwa v87, v119 dst_sel:DWORD dst_unused:UNUSED_PAD src0_sel:WORD_1
	v_cvt_f32_f16_e32 v86, v119
	v_cmp_lt_i32_e32 vcc, v155, v156
	v_cvt_f32_f16_sdwa v79, v121 dst_sel:DWORD dst_unused:UNUSED_PAD src0_sel:WORD_1
	v_cvt_f32_f16_e32 v162, v114
	v_cvt_f32_f16_sdwa v163, v114 dst_sel:DWORD dst_unused:UNUSED_PAD src0_sel:WORD_1
	v_cvt_f32_f16_e32 v164, v115
	v_cvt_f32_f16_sdwa v165, v115 dst_sel:DWORD dst_unused:UNUSED_PAD src0_sel:WORD_1
	s_waitcnt vmcnt(5)
	v_pk_mul_f32 v[62:63], v[62:63], v[86:87]
	v_add_f32_e32 v54, v68, v88
	v_add_f32_e32 v55, v72, v92
	v_add_f32_e32 v56, v69, v89
	v_add_f32_e32 v64, v73, v93
	v_add_f32_e32 v65, v70, v90
	v_add_f32_e32 v66, v74, v94
	v_add_f32_e32 v67, v71, v91
	v_add_f32_e32 v52, v52, v96
	v_add_f32_e32 v69, v53, v100
	v_mul_f32_e32 v53, 0xbfb8aa3b, v54
	v_mul_f32_e32 v54, 0xbfb8aa3b, v55
	v_mul_f32_e32 v55, 0xbfb8aa3b, v56
	v_mul_f32_e32 v56, 0xbfb8aa3b, v64
	v_mul_f32_e32 v64, 0xbfb8aa3b, v65
	v_mul_f32_e32 v65, 0xbfb8aa3b, v66
	v_mul_f32_e32 v66, 0xbfb8aa3b, v67
	v_mul_f32_e32 v52, 0xbfb8aa3b, v52
	v_exp_f32_e32 v53, v53
	v_exp_f32_e32 v54, v54
	v_exp_f32_e32 v55, v55
	v_exp_f32_e32 v56, v56
	v_exp_f32_e32 v64, v64
	v_exp_f32_e32 v66, v66
	v_exp_f32_e32 v52, v52
	v_exp_f32_e32 v65, v65
	v_add_f32_e32 v68, v75, v95
	v_mul_f32_e32 v67, 0xbfb8aa3b, v68
	v_add_f32_e32 v53, 1.0, v53
	v_add_f32_e32 v54, 1.0, v54
	v_add_f32_e32 v55, 1.0, v55
	v_add_f32_e32 v56, 1.0, v56
	v_add_f32_e32 v68, 1.0, v64
	v_add_f32_e32 v71, 1.0, v66
	v_add_f32_e32 v52, 1.0, v52
	v_add_f32_e32 v70, 1.0, v65
	v_rcp_f32_e32 v53, v53
	v_rcp_f32_e32 v64, v54
	v_rcp_f32_e32 v54, v55
	v_rcp_f32_e32 v65, v56
	v_rcp_f32_e32 v55, v68
	v_rcp_f32_e32 v56, v71
	v_rcp_f32_e32 v52, v52
	v_mul_f32_e32 v53, 0xbf1b4598, v53
	v_mul_f32_e32 v54, 0xbf1b4598, v54
	v_mul_f32_e32 v55, 0xbf1b4598, v55
	v_mul_f32_e32 v56, 0xbf1b4598, v56
	v_mul_f32_e32 v52, 0xbf1b4598, v52
	v_mul_f32_e32 v53, 0x3fb8aa3b, v53
	v_mul_f32_e32 v54, 0x3fb8aa3b, v54
	v_mul_f32_e32 v55, 0x3fb8aa3b, v55
	v_mul_f32_e32 v56, 0x3fb8aa3b, v56
	v_mul_f32_e32 v68, 0x3fb8aa3b, v52
	v_exp_f32_e32 v52, v53
	v_exp_f32_e32 v53, v54
	v_exp_f32_e32 v54, v55
	v_exp_f32_e32 v55, v56
	v_exp_f32_e32 v56, v68
	v_mul_f32_e32 v68, 0xbfb8aa3b, v69
	v_add_f32_e32 v69, v78, v97
	v_mul_f32_e32 v69, 0xbfb8aa3b, v69
	v_exp_f32_e32 v69, v69
	v_add_f32_e32 v57, v57, v101
	v_mul_f32_e32 v57, 0xbfb8aa3b, v57
	v_rcp_f32_e32 v66, v70
	v_add_f32_e32 v69, 1.0, v69
	v_rcp_f32_e32 v69, v69
	v_exp_f32_e32 v70, v57
	v_add_f32_e32 v58, v58, v102
	v_mul_f32_e32 v58, 0xbfb8aa3b, v58
	v_mul_f32_e32 v57, 0xbf1b4598, v69
	v_add_f32_e32 v69, 1.0, v70
	v_add_f32_e32 v70, v77, v98
	v_mul_f32_e32 v70, 0xbfb8aa3b, v70
	v_exp_f32_e32 v72, v70
	v_exp_f32_e32 v78, v58
	v_add_f32_e32 v58, v76, v99
	v_mul_f32_e32 v58, 0xbfb8aa3b, v58
	v_add_f32_e32 v72, 1.0, v72
	v_rcp_f32_e32 v77, v72
	v_exp_f32_e32 v76, v58
	v_mad_u32_u24 v96, s28, v169, v84
	v_cvt_f32_f16_e32 v84, v118
	v_mul_f32_e32 v77, 0xbf1b4598, v77
	v_add_f32_e32 v76, 1.0, v76
	v_mul_f32_e32 v58, 0x3fb8aa3b, v77
	v_add_f32_e32 v77, 1.0, v78
	v_rcp_f32_e32 v78, v76
	v_cvt_f32_f16_sdwa v71, v120 dst_sel:DWORD dst_unused:UNUSED_PAD src0_sel:WORD_1
	v_cvt_f32_f16_e32 v70, v120
	v_add_f32_e32 v59, v59, v103
	v_mul_f32_e32 v59, 0xbfb8aa3b, v59
	v_cndmask_b32_e32 v88, v154, v155, vcc
	v_pk_mul_f32 v[60:61], v[60:61], v[84:85]
	v_rcp_f32_e32 v76, v77
	v_mul_f32_e32 v77, 0xbf1b4598, v78
	v_exp_f32_e32 v80, v59
	v_cvt_f32_f16_e32 v78, v121
	v_lshlrev_b32_e32 v97, 2, v88
	v_pk_mul_f32 v[88:89], v[60:61], v[60:61]
	v_pk_mul_f32 v[90:91], v[62:63], v[62:63]
	v_add_f32_e32 v88, v88, v89
	s_waitcnt vmcnt(4)
	v_pk_mul_f32 v[72:73], v[104:105], v[70:71]
	v_add_f32_e32 v88, v90, v88
	v_pk_mul_f32 v[74:75], v[72:73], v[72:73]
	v_mul_f32_e32 v77, 0x3fb8aa3b, v77
	v_add_f32_e32 v88, v91, v88
	v_exp_f32_e32 v59, v77
	v_add_f32_e32 v77, 1.0, v80
	v_pk_mul_f32 v[80:81], v[106:107], v[78:79]
	v_add_f32_e32 v74, v88, v74
	v_pk_mul_f32 v[82:83], v[80:81], v[80:81]
	v_add_f32_e32 v74, v75, v74
	v_add_f32_e32 v74, v82, v74
	v_add_f32_e32 v74, v83, v74
	v_cmp_lt_i32_e32 vcc, v157, v156
	v_exp_f32_e32 v67, v67
	v_add_f32_dpp v82, v74, v74 row_ror:8 row_mask:0xf bank_mask:0xf bound_ctrl:1
	ds_bpermute_b32 v83, v97, v82
	v_cndmask_b32_e32 v74, v154, v157, vcc
	v_lshlrev_b32_e32 v88, 2, v74
	v_pk_add_f32 v[74:75], v[64:65], -1.0 op_sel_hi:[1,0]
	v_add_f32_e32 v67, 1.0, v67
	s_waitcnt lgkmcnt(0)
	v_add_f32_e32 v82, v82, v83
	ds_bpermute_b32 v83, v88, v82
	s_waitcnt vmcnt(3)
	v_pk_fma_f32 v[48:49], v[48:49], v[74:75], 1.0 op_sel_hi:[1,1,0]
	v_rcp_f32_e32 v67, v67
	v_pk_mul_f32 v[48:49], v[48:49], v[84:85]
	v_exp_f32_e32 v68, v68
	v_mul_f32_e32 v74, v48, v162
	s_waitcnt vmcnt(1)
	v_fma_f32 v84, v44, v74, 0
	s_waitcnt lgkmcnt(0)
	v_add_f32_e32 v44, v82, v83
	v_max_f32_e32 v44, 0x179abe15, v44
	v_rsq_f32_e32 v44, v44
	v_mul_f32_e32 v74, v49, v163
	v_add_f32_e32 v68, 1.0, v68
	v_fmac_f32_e32 v84, v45, v74
	v_pk_mul_f32 v[62:63], v[62:63], v[44:45] op_sel_hi:[1,0]
	v_rcp_f32_e32 v68, v68
	v_pk_mul_f32 v[74:75], v[66:67], v[62:63]
	v_pk_add_f32 v[66:67], v[66:67], -1.0 op_sel_hi:[1,0]
	v_rcp_f32_e32 v69, v69
	v_pk_fma_f32 v[50:51], v[50:51], v[66:67], 1.0 op_sel_hi:[1,1,0]
	v_pk_mul_f32 v[60:61], v[60:61], v[44:45] op_sel_hi:[1,0]
	v_pk_mul_f32 v[50:51], v[50:51], v[86:87]
	v_cvt_f32_f16_e32 v92, v110
	v_mul_f32_e32 v45, v50, v164
	v_cvt_pk_f16_f32 v48, v48, v49
	v_mul_f32_e32 v49, v51, v165
	v_fmac_f32_e32 v84, v46, v45
	v_cvt_f32_f16_sdwa v93, v110 dst_sel:DWORD dst_unused:UNUSED_PAD src0_sel:WORD_1
	v_fmac_f32_e32 v84, v47, v49
	v_cvt_pk_f16_f32 v49, v50, v51
	v_lshl_add_u32 v45, v176, 2, s27
	v_pk_add_f32 v[50:51], v[68:69], -1.0 op_sel_hi:[1,0]
	v_rcp_f32_e32 v77, v77
	v_pk_mul_f32 v[64:65], v[64:65], v[60:61]
	v_cvt_pk_f16_f32 v47, -v62, -v63
	v_cvt_pk_f16_f32 v46, -v60, -v61
	ds_write_b128 v45, v[52:55]
	v_lshl_add_u32 v45, v176, 1, v96
	v_pk_fma_f32 v[40:41], v[40:41], v[50:51], 1.0 op_sel_hi:[1,1,0]
	v_cvt_pk_f16_f32 v64, v64, v65
	v_cvt_pk_f16_f32 v65, v74, v75
	ds_write2st64_b64 v45, v[48:49], v[46:47] offset0:32 offset1:40
	ds_write2st64_b64 v45, v[64:65], v[114:115] offset0:48 offset1:56
	ds_write_b64 v45, v[116:117] offset:32768
	v_pk_mul_f32 v[46:47], v[72:73], v[44:45] op_sel_hi:[1,0]
	v_pk_mul_f32 v[40:41], v[40:41], v[70:71]
	v_pk_mul_f32 v[48:49], v[68:69], v[46:47]
	v_mul_f32_e32 v45, v40, v92
	v_cvt_f32_f16_e32 v94, v111
	v_cvt_pk_f16_f32 v48, v48, v49
	v_mul_f32_e32 v49, v41, v93
	s_waitcnt vmcnt(0)
	v_fmac_f32_e32 v84, v36, v45
	v_cvt_f32_f16_sdwa v95, v111 dst_sel:DWORD dst_unused:UNUSED_PAD src0_sel:WORD_1
	v_fmac_f32_e32 v84, v37, v49
	v_pk_add_f32 v[36:37], v[76:77], -1.0 op_sel_hi:[1,0]
	v_mul_f32_e32 v57, 0x3fb8aa3b, v57
	v_pk_fma_f32 v[36:37], v[42:43], v[36:37], 1.0 op_sel_hi:[1,1,0]
	v_exp_f32_e32 v57, v57
	v_pk_mul_f32 v[42:43], v[36:37], v[78:79]
	v_exp_f32_e32 v58, v58
	v_mul_f32_e32 v36, v42, v94
	v_mul_f32_e32 v37, v43, v95
	v_fmac_f32_e32 v84, v38, v36
	v_fmac_f32_e32 v84, v39, v37
	v_cvt_pk_f16_f32 v38, v40, v41
	s_nop 0
	v_add_f32_dpp v39, v84, v84 row_ror:8 row_mask:0xf bank_mask:0xf bound_ctrl:1
	ds_bpermute_b32 v45, v97, v39
	s_waitcnt lgkmcnt(0)
	v_pk_mul_f32 v[40:41], v[80:81], v[44:45] op_sel_hi:[1,0]
	s_nop 0
	v_pk_mul_f32 v[36:37], v[76:77], v[40:41]
	v_cvt_pk_f16_f32 v41, -v40, -v41
	v_cvt_pk_f16_f32 v49, v36, v37
	v_add_f32_e32 v36, v39, v45
	ds_bpermute_b32 v37, v88, v36
	v_cvt_pk_f16_f32 v39, v42, v43
	v_lshl_add_u32 v42, v177, 2, s27
	v_cvt_pk_f16_f32 v40, -v46, -v47
	ds_write_b128 v42, v[56:59]
	v_lshl_add_u32 v42, v177, 1, v96
	ds_write2st64_b64 v42, v[38:39], v[40:41] offset0:32 offset1:40
	ds_write2st64_b64 v42, v[48:49], v[110:111] offset0:48 offset1:56
	ds_write_b64 v42, v[112:113] offset:32768
	s_and_saveexec_b64 s[28:29], s[8:9]
	s_cbranch_execz .LBB0_954
	v_add_u32_e32 v2, v2, v175
	s_waitcnt lgkmcnt(4)
	v_add_f32_e32 v38, v36, v37
	v_mad_i64_i32 v[36:37], s[30:31], v2, 48, v[128:129]
	global_store_dword v[36:37], v38, off

.LBB0_1040:
	v_cndmask_b32_e64 v244, v235, v2, s[6:7]
	v_cndmask_b32_e64 v245, v242, v234, s[6:7]
	v_cndmask_b32_e64 v246, v2, v235, s[6:7]
	v_cndmask_b32_e64 v247, v234, v242, s[6:7]
	v_cndmask_b32_e64 v234, v240, v236, s[6:7]
	v_cndmask_b32_e64 v235, v241, v237, s[6:7]
	s_waitcnt lgkmcnt(14)
	v_mfma_f32_16x16x32_f16 v[76:79], v[76:79], v[244:247], 0
	v_cndmask_b32_e64 v236, v236, v240, s[6:7]
	v_cndmask_b32_e64 v237, v237, v241, s[6:7]
	v_add_u32_e32 v2, s69, v150
	s_waitcnt lgkmcnt(13)
	v_mfma_f32_16x16x32_f16 v[84:87], v[84:87], v[32:35], 0
	v_subrev_u32_e32 v2, 32, v2
	v_mfma_f32_16x16x32_f16 v[76:79], v[40:43], v[234:237], v[76:79]
	s_waitcnt lgkmcnt(11)
	v_mfma_f32_16x16x32_f16 v[40:43], v[48:51], v[244:247], 0
	v_mfma_f32_16x16x32_f16 v[84:87], v[44:47], v[28:31], v[84:87]
	s_waitcnt lgkmcnt(9)
	v_mfma_f32_16x16x32_f16 v[44:47], v[68:71], v[32:35], 0
	v_mfma_f32_16x16x32_f16 v[52:55], v[52:55], v[234:237], v[40:43]
	s_waitcnt lgkmcnt(7)
	v_mfma_f32_16x16x32_f16 v[40:43], v[60:63], v[244:247], 0
	v_mfma_f32_16x16x32_f16 v[56:59], v[56:59], v[28:31], v[44:47]
	s_waitcnt lgkmcnt(5)
	v_mfma_f32_16x16x32_f16 v[44:47], v[80:83], v[32:35], 0
	v_mfma_f32_16x16x32_f16 v[68:71], v[64:67], v[234:237], v[40:43]
	s_waitcnt lgkmcnt(3)
	v_mfma_f32_16x16x32_f16 v[40:43], v[88:91], v[244:247], 0
	s_waitcnt lgkmcnt(1)
	v_mfma_f32_16x16x32_f16 v[32:35], v[96:99], v[32:35], 0
	v_mfma_f32_16x16x32_f16 v[72:75], v[72:75], v[28:31], v[44:47]
	s_waitcnt lgkmcnt(0)
	v_mfma_f32_16x16x32_f16 v[64:67], v[92:95], v[28:31], v[32:35]
	s_nop 0
	v_add_u32_e32 v44, s68, v231
	v_cndmask_b32_e64 v2, v44, v2, s[2:3]
	v_mfma_f32_16x16x32_f16 v[80:83], v[36:39], v[234:237], v[40:43]
	s_branch .LBB0_1050

.LBB0_1050:
	s_add_i32 s76, s76, 1
	s_andn2_b64 vcc, exec, s[26:27]
	s_barrier
	s_cbranch_vccnz .LBB0_1027
	s_waitcnt vmcnt(6)
	v_mov_b64_e32 v[28:29], v[100:101]
	v_mov_b64_e32 v[32:33], v[104:105]
	v_mov_b64_e32 v[34:35], v[106:107]
	v_mov_b64_e32 v[30:31], v[102:103]
	global_load_dwordx4 v[88:91], v[126:127], off
	global_load_dwordx4 v[92:95], v[128:129], off
	global_load_dwordx4 v[96:99], v[126:127], off offset:64
	global_load_dwordx4 v[100:103], v[128:129], off offset:64
	global_load_dwordx4 v[60:63], v[130:131], off offset:3072
	global_load_dwordx4 v[104:107], v[130:131], off offset:3136
	global_load_dwordx4 v[48:51], v[132:133], off offset:3072
	global_load_dwordx4 v[40:43], v[132:133], off offset:3136
	global_load_dwordx4 v[44:47], v[134:135], off offset:3072
	global_load_dwordx4 v[36:39], v[134:135], off offset:3136
	v_cndmask_b32_e64 v71, v71, v79, s[6:7]
	v_cndmask_b32_e64 v70, v70, v78, s[6:7]
	v_cndmask_b32_e64 v69, v69, v77, s[6:7]
	v_cndmask_b32_e64 v68, v68, v76, s[6:7]
	v_cndmask_b32_e64 v74, v74, v86, s[6:7]
	v_cndmask_b32_e64 v73, v73, v85, s[6:7]
	v_cndmask_b32_e64 v72, v72, v84, s[6:7]
	v_cndmask_b32_e64 v52, v80, v52, s[6:7]
	v_cndmask_b32_e64 v76, v83, v55, s[6:7]
	v_cndmask_b32_e64 v77, v82, v54, s[6:7]
	v_cndmask_b32_e64 v78, v81, v53, s[6:7]
	v_cndmask_b32_e64 v59, v67, v59, s[6:7]
	v_cndmask_b32_e64 v58, v66, v58, s[6:7]
	v_cndmask_b32_e64 v57, v65, v57, s[6:7]
	v_cndmask_b32_e64 v53, v64, v56, s[6:7]
	v_cndmask_b32_e64 v75, v75, v87, s[6:7]
	s_and_b32 s27, s76, 1
	s_lshl_b32 s26, s27, 13
	s_add_i32 s26, s26, 0
	v_mov_b32_e32 v84, s26
	v_cvt_f32_f16_sdwa v85, v116 dst_sel:DWORD dst_unused:UNUSED_PAD src0_sel:WORD_1
	v_cvt_f32_f16_sdwa v87, v117 dst_sel:DWORD dst_unused:UNUSED_PAD src0_sel:WORD_1
	v_cvt_f32_f16_e32 v86, v117
	v_cmp_lt_i32_e32 vcc, v155, v156
	v_cvt_f32_f16_sdwa v79, v119 dst_sel:DWORD dst_unused:UNUSED_PAD src0_sel:WORD_1
	v_cvt_f32_f16_e32 v162, v112
	v_cvt_f32_f16_sdwa v163, v112 dst_sel:DWORD dst_unused:UNUSED_PAD src0_sel:WORD_1
	v_cvt_f32_f16_e32 v164, v113
	v_cvt_f32_f16_sdwa v165, v113 dst_sel:DWORD dst_unused:UNUSED_PAD src0_sel:WORD_1
	s_waitcnt vmcnt(5)
	v_pk_mul_f32 v[62:63], v[62:63], v[86:87]
	v_add_f32_e32 v54, v68, v88
	v_add_f32_e32 v55, v72, v92
	v_add_f32_e32 v56, v69, v89
	v_add_f32_e32 v64, v73, v93
	v_add_f32_e32 v65, v70, v90
	v_add_f32_e32 v66, v74, v94
	v_add_f32_e32 v67, v71, v91
	v_add_f32_e32 v52, v52, v96
	v_add_f32_e32 v69, v53, v100
	v_mul_f32_e32 v53, 0xbfb8aa3b, v54
	v_mul_f32_e32 v54, 0xbfb8aa3b, v55
	v_mul_f32_e32 v55, 0xbfb8aa3b, v56
	v_mul_f32_e32 v56, 0xbfb8aa3b, v64
	v_mul_f32_e32 v64, 0xbfb8aa3b, v65
	v_mul_f32_e32 v65, 0xbfb8aa3b, v66
	v_mul_f32_e32 v66, 0xbfb8aa3b, v67
	v_mul_f32_e32 v52, 0xbfb8aa3b, v52
	v_exp_f32_e32 v53, v53
	v_exp_f32_e32 v54, v54
	v_exp_f32_e32 v55, v55
	v_exp_f32_e32 v56, v56
	v_exp_f32_e32 v64, v64
	v_exp_f32_e32 v66, v66
	v_exp_f32_e32 v52, v52
	v_exp_f32_e32 v65, v65
	v_add_f32_e32 v68, v75, v95
	v_mul_f32_e32 v67, 0xbfb8aa3b, v68
	v_add_f32_e32 v53, 1.0, v53
	v_add_f32_e32 v54, 1.0, v54
	v_add_f32_e32 v55, 1.0, v55
	v_add_f32_e32 v56, 1.0, v56
	v_add_f32_e32 v68, 1.0, v64
	v_add_f32_e32 v71, 1.0, v66
	v_add_f32_e32 v52, 1.0, v52
	v_add_f32_e32 v70, 1.0, v65
	v_rcp_f32_e32 v53, v53
	v_rcp_f32_e32 v64, v54
	v_rcp_f32_e32 v54, v55
	v_rcp_f32_e32 v65, v56
	v_rcp_f32_e32 v55, v68
	v_rcp_f32_e32 v56, v71
	v_rcp_f32_e32 v52, v52
	v_mul_f32_e32 v53, 0xbf1b4598, v53
	v_mul_f32_e32 v54, 0xbf1b4598, v54
	v_mul_f32_e32 v55, 0xbf1b4598, v55
	v_mul_f32_e32 v56, 0xbf1b4598, v56
	v_mul_f32_e32 v52, 0xbf1b4598, v52
	v_mul_f32_e32 v53, 0x3fb8aa3b, v53
	v_mul_f32_e32 v54, 0x3fb8aa3b, v54
	v_mul_f32_e32 v55, 0x3fb8aa3b, v55
	v_mul_f32_e32 v56, 0x3fb8aa3b, v56
	v_mul_f32_e32 v68, 0x3fb8aa3b, v52
	v_exp_f32_e32 v52, v53
	v_exp_f32_e32 v53, v54
	v_exp_f32_e32 v54, v55
	v_exp_f32_e32 v55, v56
	v_exp_f32_e32 v56, v68
	v_mul_f32_e32 v68, 0xbfb8aa3b, v69
	v_add_f32_e32 v69, v78, v97
	v_mul_f32_e32 v69, 0xbfb8aa3b, v69
	v_exp_f32_e32 v69, v69
	v_add_f32_e32 v57, v57, v101
	v_mul_f32_e32 v57, 0xbfb8aa3b, v57
	v_rcp_f32_e32 v66, v70
	v_add_f32_e32 v69, 1.0, v69
	v_rcp_f32_e32 v69, v69
	v_exp_f32_e32 v70, v57
	v_add_f32_e32 v58, v58, v102
	v_mul_f32_e32 v58, 0xbfb8aa3b, v58
	v_mul_f32_e32 v57, 0xbf1b4598, v69
	v_add_f32_e32 v69, 1.0, v70
	v_add_f32_e32 v70, v77, v98
	v_mul_f32_e32 v70, 0xbfb8aa3b, v70
	v_exp_f32_e32 v72, v70
	v_exp_f32_e32 v78, v58
	v_add_f32_e32 v58, v76, v99
	v_mul_f32_e32 v58, 0xbfb8aa3b, v58
	v_add_f32_e32 v72, 1.0, v72
	v_rcp_f32_e32 v77, v72
	v_exp_f32_e32 v76, v58
	v_mad_u32_u24 v96, s27, v169, v84
	v_cvt_f32_f16_e32 v84, v116
	v_mul_f32_e32 v77, 0xbf1b4598, v77
	v_add_f32_e32 v76, 1.0, v76
	v_mul_f32_e32 v58, 0x3fb8aa3b, v77
	v_add_f32_e32 v77, 1.0, v78
	v_rcp_f32_e32 v78, v76
	v_cvt_f32_f16_sdwa v71, v118 dst_sel:DWORD dst_unused:UNUSED_PAD src0_sel:WORD_1
	v_cvt_f32_f16_e32 v70, v118
	v_add_f32_e32 v59, v59, v103
	v_mul_f32_e32 v59, 0xbfb8aa3b, v59
	v_cndmask_b32_e32 v88, v154, v155, vcc
	v_pk_mul_f32 v[60:61], v[60:61], v[84:85]
	v_rcp_f32_e32 v76, v77
	v_mul_f32_e32 v77, 0xbf1b4598, v78
	v_exp_f32_e32 v80, v59
	v_cvt_f32_f16_e32 v78, v119
	v_lshlrev_b32_e32 v97, 2, v88
	v_pk_mul_f32 v[88:89], v[60:61], v[60:61]
	v_pk_mul_f32 v[90:91], v[62:63], v[62:63]
	v_add_f32_e32 v88, v88, v89
	s_waitcnt vmcnt(4)
	v_pk_mul_f32 v[72:73], v[104:105], v[70:71]
	v_add_f32_e32 v88, v90, v88
	v_pk_mul_f32 v[74:75], v[72:73], v[72:73]
	v_mul_f32_e32 v77, 0x3fb8aa3b, v77
	v_add_f32_e32 v88, v91, v88
	v_exp_f32_e32 v59, v77
	v_add_f32_e32 v77, 1.0, v80
	v_pk_mul_f32 v[80:81], v[106:107], v[78:79]
	v_add_f32_e32 v74, v88, v74
	v_pk_mul_f32 v[82:83], v[80:81], v[80:81]
	v_add_f32_e32 v74, v75, v74
	v_add_f32_e32 v74, v82, v74
	v_add_f32_e32 v74, v83, v74
	v_cmp_lt_i32_e32 vcc, v157, v156
	v_exp_f32_e32 v67, v67
	v_add_f32_dpp v82, v74, v74 row_ror:8 row_mask:0xf bank_mask:0xf bound_ctrl:1
	ds_bpermute_b32 v83, v97, v82
	v_cndmask_b32_e32 v74, v154, v157, vcc
	v_lshlrev_b32_e32 v88, 2, v74
	v_pk_add_f32 v[74:75], v[64:65], -1.0 op_sel_hi:[1,0]
	v_add_f32_e32 v67, 1.0, v67
	s_waitcnt lgkmcnt(0)
	v_add_f32_e32 v82, v82, v83
	ds_bpermute_b32 v83, v88, v82
	s_waitcnt vmcnt(3)
	v_pk_fma_f32 v[48:49], v[48:49], v[74:75], 1.0 op_sel_hi:[1,1,0]
	v_rcp_f32_e32 v67, v67
	v_pk_mul_f32 v[48:49], v[48:49], v[84:85]
	v_exp_f32_e32 v68, v68
	v_mul_f32_e32 v74, v48, v162
	s_waitcnt vmcnt(1)
	v_fma_f32 v84, v44, v74, 0
	s_waitcnt lgkmcnt(0)
	v_add_f32_e32 v44, v82, v83
	v_max_f32_e32 v44, 0x179abe15, v44
	v_rsq_f32_e32 v44, v44
	v_mul_f32_e32 v74, v49, v163
	v_add_f32_e32 v68, 1.0, v68
	v_fmac_f32_e32 v84, v45, v74
	v_pk_mul_f32 v[62:63], v[62:63], v[44:45] op_sel_hi:[1,0]
	v_rcp_f32_e32 v68, v68
	v_pk_mul_f32 v[74:75], v[66:67], v[62:63]
	v_pk_add_f32 v[66:67], v[66:67], -1.0 op_sel_hi:[1,0]
	v_rcp_f32_e32 v69, v69
	v_pk_fma_f32 v[50:51], v[50:51], v[66:67], 1.0 op_sel_hi:[1,1,0]
	v_pk_mul_f32 v[60:61], v[60:61], v[44:45] op_sel_hi:[1,0]
	v_pk_mul_f32 v[50:51], v[50:51], v[86:87]
	v_cvt_f32_f16_e32 v92, v108
	v_mul_f32_e32 v45, v50, v164
	v_cvt_pk_f16_f32 v48, v48, v49
	v_mul_f32_e32 v49, v51, v165
	v_fmac_f32_e32 v84, v46, v45
	v_cvt_f32_f16_sdwa v93, v108 dst_sel:DWORD dst_unused:UNUSED_PAD src0_sel:WORD_1
	v_fmac_f32_e32 v84, v47, v49
	v_cvt_pk_f16_f32 v49, v50, v51
	v_lshl_add_u32 v45, v152, 2, s26
	v_pk_add_f32 v[50:51], v[68:69], -1.0 op_sel_hi:[1,0]
	v_rcp_f32_e32 v77, v77
	v_pk_mul_f32 v[64:65], v[64:65], v[60:61]
	v_cvt_pk_f16_f32 v47, -v62, -v63
	v_cvt_pk_f16_f32 v46, -v60, -v61
	ds_write_b128 v45, v[52:55]
	v_lshl_add_u32 v45, v152, 1, v96
	v_pk_fma_f32 v[40:41], v[40:41], v[50:51], 1.0 op_sel_hi:[1,1,0]
	v_cvt_pk_f16_f32 v64, v64, v65
	v_cvt_pk_f16_f32 v65, v74, v75
	ds_write2st64_b64 v45, v[48:49], v[46:47] offset0:32 offset1:40
	ds_write2st64_b64 v45, v[64:65], v[112:113] offset0:48 offset1:56
	ds_write_b64 v45, v[114:115] offset:32768
	v_pk_mul_f32 v[46:47], v[72:73], v[44:45] op_sel_hi:[1,0]
	v_pk_mul_f32 v[40:41], v[40:41], v[70:71]
	v_pk_mul_f32 v[48:49], v[68:69], v[46:47]
	v_mul_f32_e32 v45, v40, v92
	v_cvt_f32_f16_e32 v94, v109
	v_cvt_pk_f16_f32 v48, v48, v49
	v_mul_f32_e32 v49, v41, v93
	s_waitcnt vmcnt(0)
	v_fmac_f32_e32 v84, v36, v45
	v_cvt_f32_f16_sdwa v95, v109 dst_sel:DWORD dst_unused:UNUSED_PAD src0_sel:WORD_1
	v_fmac_f32_e32 v84, v37, v49
	v_pk_add_f32 v[36:37], v[76:77], -1.0 op_sel_hi:[1,0]
	v_mul_f32_e32 v57, 0x3fb8aa3b, v57
	v_pk_fma_f32 v[36:37], v[42:43], v[36:37], 1.0 op_sel_hi:[1,1,0]
	v_exp_f32_e32 v57, v57
	v_pk_mul_f32 v[42:43], v[36:37], v[78:79]
	v_exp_f32_e32 v58, v58
	v_mul_f32_e32 v36, v42, v94
	v_mul_f32_e32 v37, v43, v95
	v_fmac_f32_e32 v84, v38, v36
	v_fmac_f32_e32 v84, v39, v37
	v_cvt_pk_f16_f32 v38, v40, v41
	s_nop 0
	v_add_f32_dpp v39, v84, v84 row_ror:8 row_mask:0xf bank_mask:0xf bound_ctrl:1
	ds_bpermute_b32 v45, v97, v39
	s_waitcnt lgkmcnt(0)
	v_pk_mul_f32 v[40:41], v[80:81], v[44:45] op_sel_hi:[1,0]
	s_nop 0
	v_pk_mul_f32 v[36:37], v[76:77], v[40:41]
	v_cvt_pk_f16_f32 v41, -v40, -v41
	v_cvt_pk_f16_f32 v49, v36, v37
	v_add_f32_e32 v36, v39, v45
	ds_bpermute_b32 v37, v88, v36
	v_cvt_pk_f16_f32 v39, v42, v43
	v_lshl_add_u32 v42, v173, 2, s26
	v_cvt_pk_f16_f32 v40, -v46, -v47
	ds_write_b128 v42, v[56:59]
	v_lshl_add_u32 v42, v173, 1, v96
	ds_write2st64_b64 v42, v[38:39], v[40:41] offset0:32 offset1:40
	ds_write2st64_b64 v42, v[48:49], v[108:109] offset0:48 offset1:56
	ds_write_b64 v42, v[110:111] offset:32768
	s_and_saveexec_b64 s[26:27], s[8:9]
	s_cbranch_execz .LBB0_1053
	v_add_u32_e32 v2, v2, v151
	s_waitcnt lgkmcnt(4)
	v_add_f32_e32 v38, v36, v37
	v_mad_i64_i32 v[36:37], s[28:29], v2, 48, v[124:125]
	global_store_dword v[36:37], v38, off
